# hand-written pipelined attention for latent items + blocked G layout for w2 GEMM A operand + WG stagger
# speedup vs baseline: 1.0909x; 1.0482x over previous
; DI void phase_attn(const Params& p, int layer, char* smem) {
;   const int n_lat = 96 * 32, n_ctx = (layer == 0) ? 96 * 2 : 0;
;   for (int it = blockIdx.x; it < n_lat + n_ctx; it += gridDim.x) {
;     int combo, qb;
;     if (it < n_lat) { int xc = it & 7, j = it >> 3; combo = (j >> 5) * 8 + xc; qb = 2 + (j & 31); }
;     else { int r = it - n_lat; combo = r >> 1; qb = r & 1; }
;     const int type = combo / 48, bh = combo % 48;
;     attn_dispatch(p, type, bh / 6, bh % 6, qb, smem);
;   }
.LBB0_1445:
	s_or_b64 exec, exec, s[0:1]
	v_readlane_b32 s0, v234, 23
	v_readlane_b32 s1, v234, 24
	s_and_b64 s[0:1], s[0:1], exec
	s_movk_i32 s0, 0xc00
	s_cselect_b32 s12, s0, 0xcc0
	s_cmp_ge_i32 s51, s12
	s_mov_b32 s13, s51
	s_waitcnt lgkmcnt(0)
	s_barrier
	s_branch .Lat_entry

; template <int EPI>
; DI void gemm_phase(const Params& p, int layer, const bf16_t* __restrict__ A, int lda, const bf16_t* __restrict__ Bt, int ldb, int K, int MT, int NT,
;                    char* smem, bool rev = false) {
;     ...
;   const int nk = K >> 6;
;   const int soff = lr * LDT + lc;
;   const int aoff = (wr * 64 + (lane & 31)) * LDT + (lane >> 5) * 8;
;   const int boff = (wc * 64 + (lane & 31)) * LDT + (lane >> 5) * 8;
;   int mt, nt; tile_map(t, MT, NT, mt, nt);
;   int m0 = mt * 128, n0 = nt * 128;
;   const bf16_t* Agl = A + (size_t)(m0 + lr) * lda + lc;
;   const bf16_t* Bgl = Bt + (size_t)(n0 + lr) * ldb + lc;
;     ...
;   G_LOAD(p, 0)
;   G_LOAD(q, 64)
;   for (;;) {
;     G_WRITE(p, 0)
;     __syncthreads();
;     if (nk > 2) G_LOAD(p, 128)
;     f32x16 acc[2][2];
; #pragma unroll
;     for (int i = 0; i < 2; ++i)
; #pragma unroll
;       for (int j = 0; j < 2; ++j)
; #pragma unroll
;         for (int r = 0; r < 16; ++r) acc[i][j][r] = 0.f;
;     for (int kt = 0; kt < nk; kt += 2) {
;       G_COMPUTE(0)
;       G_WRITE(q, 1)
;       __syncthreads();
;       if (kt + 3 < nk) G_LOAD(q, (kt + 3) << 6)
;       G_COMPUTE(1)
.Lmg_par_2:
	s_add_u32 s54, s24, 0x15980000
	s_addc_u32 s55, s25, 0
	s_movk_i32 s58, 0x800
	s_movk_i32 s59, 0x800
	s_mov_b32 s81, 0x40
	s_mov_b32 s48, 0x40
	s_movk_i32 s60, 32
	s_movk_i32 s62, 15
	s_movk_i32 s69, 9363
	s_branch .Lmg_pare_6
.Lmg_par_3:
	s_mov_b32 s54, s24
	s_mov_b32 s55, s25
	s_movk_i32 s58, 0x800
	s_movk_i32 s59, 0x800
	s_mov_b32 s81, 0x40
	s_mov_b32 s48, 0x40
	s_movk_i32 s60, 32
	s_movk_i32 s62, 8
	s_movk_i32 s69, 8192
	s_add_u32 s56, s56, 0x3c0000
	s_addc_u32 s57, s57, 0
	s_branch .Lmg_pare_6
.Lmg_par_4:
	s_add_u32 s54, s24, 0x15980000
	s_addc_u32 s55, s25, 0
	s_movk_i32 s58, 0x800
	s_movk_i32 s59, 0x800
	s_mov_b32 s81, 0x40
	s_mov_b32 s48, 0x40
	s_movk_i32 s60, 32
	s_movk_i32 s62, 44
	s_movk_i32 s69, 16384
	s_add_u32 s56, s56, 0x5c0000
	s_addc_u32 s57, s57, 0
	s_branch .Lmg_pare_6
.Lmg_par_5:
	s_mov_b32 s54, s24
	s_mov_b32 s55, s25
	s_movk_i32 s58, 0x40
	s_movk_i32 s59, 0x1600
	s_mov_b32 s81, 0x220000
	s_mov_b32 s48, 0x40
	s_movk_i32 s60, 88
	s_movk_i32 s62, 8
	s_movk_i32 s69, 8192
	s_add_u32 s56, s56, 0x10c0000
	s_addc_u32 s57, s57, 0
.Lmg_pare_6:
	s_lshl_b32 s0, s61, 3
	s_mul_i32 s64, s0, s62
	v_lshrrev_b32_e32 v184, 2, v140
	v_and_b32_e32 v185, 3, v140
	v_bfe_u32 v186, v140, 4, 2
	v_xor_b32_e32 v185, v185, v186
	v_lshlrev_b32_e32 v185, 4, v185
	s_lshl_b32 s0, s77, 6
	v_add_u32_e32 v186, s0, v184
	v_mul_lo_u32 v186, v186, s58
	v_add_u32_e32 v213, v186, v185
	s_lshl_b32 s0, s58, 4
	s_sub_u32 s0, s0, 0x400
	v_add_u32_e32 v214, s0, v213
	v_add_u32_e32 v215, s0, v214
	v_add_u32_e32 v216, s0, v215
	s_lshl_b32 s0, s77, 5
	v_add_u32_e32 v186, s0, v184
	v_mul_lo_u32 v186, v186, s59
	v_add_u32_e32 v217, v186, v185
	s_lshl_b32 s0, s59, 4
	s_sub_u32 s0, s0, 0x400
	v_add_u32_e32 v218, s0, v217
	v_bfe_u32 v184, v140, 2, 2
	v_xor_b32_e32 v185, v184, v228
	v_xor_b32_e32 v186, 2, v185
	v_lshlrev_b32_e32 v187, 6, v227
	v_lshl_add_u32 v185, v185, 4, v187
	v_lshl_add_u32 v186, v186, 4, v187
	s_mul_i32 s0, s78, 0x3000
	v_add_u32_e32 v219, s0, v185
	v_add_u32_e32 v220, s0, v186
	s_mul_i32 s0, s79, 0x3000
	s_add_u32 s0, s0, 0x1000
	v_add_u32_e32 v221, s0, v185
	v_add_u32_e32 v222, s0, v186
	s_getreg_b32 s0, hwreg(HW_REG_HW_ID, 16, 4)
	s_and_b32 s0, s0, 1
	s_cmp_eq_u32 s0, 0
	s_cbranch_scc1 .Lmg_stag_7
	s_sleep 8
.Lmg_stag_7:
.Lmg_tile:
	s_cmp_ge_u32 s66, s64
	s_cbranch_scc1 .Lmg_done
	s_and_b32 s0, s66, 7
	s_lshr_b32 s1, s66, 3
	s_lshr_b32 s10, s1, 3
	s_mul_i32 s10, s10, s63
	s_lshr_b32 s10, s10, 16
	s_lshr_b32 s11, s62, 3
	s_mov_b32 s12, 8
	s_mov_b32 s13, 0x2000
	s_cmp_ge_u32 s10, s11
	s_cbranch_scc0 .Lmg_tm_8
	s_mov_b32 s10, s11
	s_and_b32 s12, s62, 7
	s_mov_b32 s13, s69
.Lmg_tm_8:
	s_lshl_b32 s28, s61, 3
	s_mul_i32 s28, s28, s10
	s_sub_u32 s28, s1, s28
	s_mul_i32 s29, s28, s13
	s_lshr_b32 s29, s29, 16
	s_mul_i32 s44, s29, s12
	s_sub_u32 s44, s28, s44
	s_mul_i32 s0, s0, s61
	s_add_u32 s0, s0, s29
	s_lshl_b32 s10, s10, 3
	s_add_u32 s10, s10, s44
	s_lshl_b32 s67, s0, 8
	s_lshl_b32 s68, s10, 7
	s_mul_i32 s0, s67, s58
	s_add_u32 s70, s54, s0
	s_addc_u32 s71, s55, 0
	s_mul_i32 s0, s68, s59
	s_add_u32 s72, s56, s0
	s_addc_u32 s73, s57, 0
	s_barrier
	s_mov_b32 s74, s80
	s_mov_b32 m0, s74
	s_nop 0
	global_load_lds_dwordx4 v213, s[70:71] offset:0
	global_load_lds_dwordx4 v214, s[70:71] offset:1024
	global_load_lds_dwordx4 v215, s[70:71] offset:2048
	global_load_lds_dwordx4 v216, s[70:71] offset:3072
	s_add_u32 m0, s74, 0x1000
	s_nop 0
	global_load_lds_dwordx4 v217, s[72:73] offset:0
	global_load_lds_dwordx4 v218, s[72:73] offset:1024
	s_add_u32 s70, s70, s81
	s_addc_u32 s71, s71, 0
	s_add_u32 s72, s72, s48
	s_addc_u32 s73, s73, 0
	s_add_u32 s74, s80, 0x6000
	s_mov_b32 m0, s74
	s_nop 0
	global_load_lds_dwordx4 v213, s[70:71] offset:0
	global_load_lds_dwordx4 v214, s[70:71] offset:1024
	global_load_lds_dwordx4 v215, s[70:71] offset:2048
	global_load_lds_dwordx4 v216, s[70:71] offset:3072
	s_add_u32 m0, s74, 0x1000
	s_nop 0
	global_load_lds_dwordx4 v217, s[72:73] offset:0
	global_load_lds_dwordx4 v218, s[72:73] offset:1024
	s_add_u32 s70, s70, s81
	s_addc_u32 s71, s71, 0
	s_add_u32 s72, s72, s48
	s_addc_u32 s73, s73, 0
	s_add_u32 s74, s80, 0xc000
	s_mov_b32 s75, 0
	v_mov_b32_e32 v223, v219
	v_mov_b32_e32 v225, v221
	v_mov_b32_e32 v224, v220
	v_mov_b32_e32 v226, v222
	s_sub_u32 s76, s60, 3
	s_waitcnt vmcnt(6)
	s_barrier
	ds_read_b128 v[128:131], v225
	ds_read_b128 v[132:135], v225 offset:6144
	ds_read_b128 v[144:147], v223
	ds_read_b128 v[148:151], v223 offset:2048
	ds_read_b128 v[152:155], v223 offset:6144
	ds_read_b128 v[156:159], v223 offset:8192
	ds_read_b128 v[160:163], v226
	ds_read_b128 v[164:167], v226 offset:6144
	ds_read_b128 v[168:171], v224
	ds_read_b128 v[172:175], v224 offset:2048
	ds_read_b128 v[176:179], v224 offset:6144
	ds_read_b128 v[180:183], v224 offset:8192
	s_add_u32 s75, s75, 0x6000
	s_cmp_eq_u32 s75, 0x12000
	s_cselect_b32 s75, 0, s75
	s_mov_b32 m0, s74
	s_waitcnt lgkmcnt(9)
	v_mfma_f32_32x32x16_bf16 v[0:15], v[144:147], v[128:131], 0
	v_mfma_f32_32x32x16_bf16 v[16:31], v[144:147], v[132:135], 0
	global_load_lds_dwordx4 v213, s[70:71] offset:0
	s_waitcnt lgkmcnt(8)
	v_mfma_f32_32x32x16_bf16 v[32:47], v[148:151], v[128:131], 0
	v_mfma_f32_32x32x16_bf16 v[48:63], v[148:151], v[132:135], 0
	global_load_lds_dwordx4 v214, s[70:71] offset:1024
	s_waitcnt lgkmcnt(7)
	v_mfma_f32_32x32x16_bf16 v[64:79], v[152:155], v[128:131], 0
	v_mfma_f32_32x32x16_bf16 v[80:95], v[152:155], v[132:135], 0
	global_load_lds_dwordx4 v215, s[70:71] offset:2048
	s_waitcnt lgkmcnt(6)
	v_mfma_f32_32x32x16_bf16 v[96:111], v[156:159], v[128:131], 0
	v_mfma_f32_32x32x16_bf16 v[112:127], v[156:159], v[132:135], 0
	global_load_lds_dwordx4 v216, s[70:71] offset:3072
	s_add_u32 m0, s74, 0x1000
	s_waitcnt lgkmcnt(3)
	v_mfma_f32_32x32x16_bf16 v[0:15], v[168:171], v[160:163], v[0:15]
	v_mfma_f32_32x32x16_bf16 v[16:31], v[168:171], v[164:167], v[16:31]
	global_load_lds_dwordx4 v217, s[72:73] offset:0
	s_waitcnt lgkmcnt(2)
	v_mfma_f32_32x32x16_bf16 v[32:47], v[172:175], v[160:163], v[32:47]
	v_mfma_f32_32x32x16_bf16 v[48:63], v[172:175], v[164:167], v[48:63]
	global_load_lds_dwordx4 v218, s[72:73] offset:1024
	s_add_u32 s70, s70, s81
	s_addc_u32 s71, s71, 0
	s_add_u32 s72, s72, s48
	s_addc_u32 s73, s73, 0
	s_waitcnt lgkmcnt(1)
	v_mfma_f32_32x32x16_bf16 v[64:79], v[176:179], v[160:163], v[64:79]
	v_mfma_f32_32x32x16_bf16 v[80:95], v[176:179], v[164:167], v[80:95]
	v_add_u32_e32 v223, s75, v219
	v_add_u32_e32 v225, s75, v221
	v_add_u32_e32 v224, s75, v220
	v_add_u32_e32 v226, s75, v222
	s_waitcnt lgkmcnt(0)
	v_mfma_f32_32x32x16_bf16 v[96:111], v[180:183], v[160:163], v[96:111]
	v_mfma_f32_32x32x16_bf16 v[112:127], v[180:183], v[164:167], v[112:127]
	s_add_u32 s74, s74, 0x6000
	s_sub_u32 s1, s74, 0x12000
	s_add_u32 s0, s80, 0x12000
	s_cmp_ge_u32 s74, s0
	s_cselect_b32 s74, s1, s74
; template <int EPI>
; DI void gemm_phase(const Params& p, int layer, const bf16_t* __restrict__ A, int lda, const bf16_t* __restrict__ Bt, int ldb, int K, int MT, int NT,
;                    char* smem, bool rev = false) {
;     ...
;     for (int kt = 0; kt < nk; kt += 2) {
;       G_COMPUTE(0)
;       G_WRITE(q, 1)
;       __syncthreads();
;       if (kt + 3 < nk) G_LOAD(q, (kt + 3) << 6)
;       G_COMPUTE(1)
;       if (kt + 2 < nk) G_WRITE(p, 0)
;       __syncthreads();
;       if (kt + 4 < nk) G_LOAD(p, (kt + 4) << 6)
;     }
.Lmg_kloop:
	s_waitcnt vmcnt(6)
	s_barrier
	ds_read_b128 v[128:131], v225
	ds_read_b128 v[132:135], v225 offset:6144
	ds_read_b128 v[144:147], v223
	ds_read_b128 v[148:151], v223 offset:2048
	ds_read_b128 v[152:155], v223 offset:6144
	ds_read_b128 v[156:159], v223 offset:8192
	ds_read_b128 v[160:163], v226
	ds_read_b128 v[164:167], v226 offset:6144
	ds_read_b128 v[168:171], v224
	ds_read_b128 v[172:175], v224 offset:2048
	ds_read_b128 v[176:179], v224 offset:6144
	ds_read_b128 v[180:183], v224 offset:8192
	s_add_u32 s75, s75, 0x6000
	s_cmp_eq_u32 s75, 0x12000
	s_cselect_b32 s75, 0, s75
	s_mov_b32 m0, s74
	s_waitcnt lgkmcnt(9)
	v_mfma_f32_32x32x16_bf16 v[0:15], v[144:147], v[128:131], v[0:15]
	v_mfma_f32_32x32x16_bf16 v[16:31], v[144:147], v[132:135], v[16:31]
	global_load_lds_dwordx4 v213, s[70:71] offset:0
	s_waitcnt lgkmcnt(8)
	v_mfma_f32_32x32x16_bf16 v[32:47], v[148:151], v[128:131], v[32:47]
	v_mfma_f32_32x32x16_bf16 v[48:63], v[148:151], v[132:135], v[48:63]
	global_load_lds_dwordx4 v214, s[70:71] offset:1024
	s_waitcnt lgkmcnt(7)
	v_mfma_f32_32x32x16_bf16 v[64:79], v[152:155], v[128:131], v[64:79]
	v_mfma_f32_32x32x16_bf16 v[80:95], v[152:155], v[132:135], v[80:95]
	global_load_lds_dwordx4 v215, s[70:71] offset:2048
	s_waitcnt lgkmcnt(6)
	v_mfma_f32_32x32x16_bf16 v[96:111], v[156:159], v[128:131], v[96:111]
	v_mfma_f32_32x32x16_bf16 v[112:127], v[156:159], v[132:135], v[112:127]
	global_load_lds_dwordx4 v216, s[70:71] offset:3072
	s_add_u32 m0, s74, 0x1000
	s_waitcnt lgkmcnt(3)
	v_mfma_f32_32x32x16_bf16 v[0:15], v[168:171], v[160:163], v[0:15]
	v_mfma_f32_32x32x16_bf16 v[16:31], v[168:171], v[164:167], v[16:31]
	global_load_lds_dwordx4 v217, s[72:73] offset:0
	s_waitcnt lgkmcnt(2)
	v_mfma_f32_32x32x16_bf16 v[32:47], v[172:175], v[160:163], v[32:47]
	v_mfma_f32_32x32x16_bf16 v[48:63], v[172:175], v[164:167], v[48:63]
	global_load_lds_dwordx4 v218, s[72:73] offset:1024
	s_add_u32 s70, s70, s81
	s_addc_u32 s71, s71, 0
	s_add_u32 s72, s72, s48
	s_addc_u32 s73, s73, 0
	s_waitcnt lgkmcnt(1)
	v_mfma_f32_32x32x16_bf16 v[64:79], v[176:179], v[160:163], v[64:79]
	v_mfma_f32_32x32x16_bf16 v[80:95], v[176:179], v[164:167], v[80:95]
	v_add_u32_e32 v223, s75, v219
	v_add_u32_e32 v225, s75, v221
	v_add_u32_e32 v224, s75, v220
	v_add_u32_e32 v226, s75, v222
	s_waitcnt lgkmcnt(0)
	v_mfma_f32_32x32x16_bf16 v[96:111], v[180:183], v[160:163], v[96:111]
	v_mfma_f32_32x32x16_bf16 v[112:127], v[180:183], v[164:167], v[112:127]
	s_add_u32 s74, s74, 0x6000
	s_sub_u32 s1, s74, 0x12000
	s_add_u32 s0, s80, 0x12000
	s_cmp_ge_u32 s74, s0
	s_cselect_b32 s74, s1, s74
	s_sub_u32 s76, s76, 1
	s_cmp_lg_u32 s76, 0
	s_cbranch_scc1 .Lmg_kloop
	s_waitcnt vmcnt(6)
	s_barrier
	ds_read_b128 v[128:131], v225
	ds_read_b128 v[132:135], v225 offset:6144
	ds_read_b128 v[144:147], v223
	ds_read_b128 v[148:151], v223 offset:2048
	ds_read_b128 v[152:155], v223 offset:6144
	ds_read_b128 v[156:159], v223 offset:8192
	ds_read_b128 v[160:163], v226
	ds_read_b128 v[164:167], v226 offset:6144
	ds_read_b128 v[168:171], v224
	ds_read_b128 v[172:175], v224 offset:2048
	ds_read_b128 v[176:179], v224 offset:6144
	ds_read_b128 v[180:183], v224 offset:8192
	s_add_u32 s75, s75, 0x6000
	s_cmp_eq_u32 s75, 0x12000
	s_cselect_b32 s75, 0, s75
	s_waitcnt lgkmcnt(9)
	v_mfma_f32_32x32x16_bf16 v[0:15], v[144:147], v[128:131], v[0:15]
	v_mfma_f32_32x32x16_bf16 v[16:31], v[144:147], v[132:135], v[16:31]
	s_waitcnt lgkmcnt(8)
	v_mfma_f32_32x32x16_bf16 v[32:47], v[148:151], v[128:131], v[32:47]
	v_mfma_f32_32x32x16_bf16 v[48:63], v[148:151], v[132:135], v[48:63]
	s_waitcnt lgkmcnt(7)
	v_mfma_f32_32x32x16_bf16 v[64:79], v[152:155], v[128:131], v[64:79]
	v_mfma_f32_32x32x16_bf16 v[80:95], v[152:155], v[132:135], v[80:95]
	s_waitcnt lgkmcnt(6)
	v_mfma_f32_32x32x16_bf16 v[96:111], v[156:159], v[128:131], v[96:111]
	v_mfma_f32_32x32x16_bf16 v[112:127], v[156:159], v[132:135], v[112:127]
	s_waitcnt lgkmcnt(3)
	v_mfma_f32_32x32x16_bf16 v[0:15], v[168:171], v[160:163], v[0:15]
	v_mfma_f32_32x32x16_bf16 v[16:31], v[168:171], v[164:167], v[16:31]
	s_waitcnt lgkmcnt(2)
	v_mfma_f32_32x32x16_bf16 v[32:47], v[172:175], v[160:163], v[32:47]
	v_mfma_f32_32x32x16_bf16 v[48:63], v[172:175], v[164:167], v[48:63]
	s_waitcnt lgkmcnt(1)
	v_mfma_f32_32x32x16_bf16 v[64:79], v[176:179], v[160:163], v[64:79]
	v_mfma_f32_32x32x16_bf16 v[80:95], v[176:179], v[164:167], v[80:95]
	v_add_u32_e32 v223, s75, v219
	v_add_u32_e32 v225, s75, v221
	v_add_u32_e32 v224, s75, v220
	v_add_u32_e32 v226, s75, v222
	s_waitcnt lgkmcnt(0)
	v_mfma_f32_32x32x16_bf16 v[96:111], v[180:183], v[160:163], v[96:111]
	v_mfma_f32_32x32x16_bf16 v[112:127], v[180:183], v[164:167], v[112:127]
	s_waitcnt vmcnt(0)
	s_barrier
	ds_read_b128 v[128:131], v225
	ds_read_b128 v[132:135], v225 offset:6144
	ds_read_b128 v[144:147], v223
	ds_read_b128 v[148:151], v223 offset:2048
	ds_read_b128 v[152:155], v223 offset:6144
	ds_read_b128 v[156:159], v223 offset:8192
	ds_read_b128 v[160:163], v226
	ds_read_b128 v[164:167], v226 offset:6144
	ds_read_b128 v[168:171], v224
	ds_read_b128 v[172:175], v224 offset:2048
	ds_read_b128 v[176:179], v224 offset:6144
	ds_read_b128 v[180:183], v224 offset:8192
	s_add_u32 s75, s75, 0x6000
	s_cmp_eq_u32 s75, 0x12000
	s_cselect_b32 s75, 0, s75
	s_waitcnt lgkmcnt(9)
	v_mfma_f32_32x32x16_bf16 v[0:15], v[144:147], v[128:131], v[0:15]
	v_mfma_f32_32x32x16_bf16 v[16:31], v[144:147], v[132:135], v[16:31]
	s_waitcnt lgkmcnt(8)
	v_mfma_f32_32x32x16_bf16 v[32:47], v[148:151], v[128:131], v[32:47]
	v_mfma_f32_32x32x16_bf16 v[48:63], v[148:151], v[132:135], v[48:63]
	s_waitcnt lgkmcnt(7)
	v_mfma_f32_32x32x16_bf16 v[64:79], v[152:155], v[128:131], v[64:79]
	v_mfma_f32_32x32x16_bf16 v[80:95], v[152:155], v[132:135], v[80:95]
	s_waitcnt lgkmcnt(6)
	v_mfma_f32_32x32x16_bf16 v[96:111], v[156:159], v[128:131], v[96:111]
	v_mfma_f32_32x32x16_bf16 v[112:127], v[156:159], v[132:135], v[112:127]
	s_waitcnt lgkmcnt(3)
	v_mfma_f32_32x32x16_bf16 v[0:15], v[168:171], v[160:163], v[0:15]
	v_mfma_f32_32x32x16_bf16 v[16:31], v[168:171], v[164:167], v[16:31]
	s_waitcnt lgkmcnt(2)
	v_mfma_f32_32x32x16_bf16 v[32:47], v[172:175], v[160:163], v[32:47]
	v_mfma_f32_32x32x16_bf16 v[48:63], v[172:175], v[164:167], v[48:63]
	s_waitcnt lgkmcnt(1)
	v_mfma_f32_32x32x16_bf16 v[64:79], v[176:179], v[160:163], v[64:79]
	v_mfma_f32_32x32x16_bf16 v[80:95], v[176:179], v[164:167], v[80:95]
	v_add_u32_e32 v223, s75, v219
	v_add_u32_e32 v225, s75, v221
	v_add_u32_e32 v224, s75, v220
	v_add_u32_e32 v226, s75, v222
	s_waitcnt lgkmcnt(0)
	v_mfma_f32_32x32x16_bf16 v[96:111], v[180:183], v[160:163], v[96:111]
	v_mfma_f32_32x32x16_bf16 v[112:127], v[180:183], v[164:167], v[112:127]

; DI bf16_t f2bf(float x) { return (bf16_t)(pack2(x, x) & 0xffffu); }
; DI int crow(int reg, int h) { return (reg & 3) + 8 * (reg >> 2) + 4 * h; }
; DI float silu_f(float x) { return x * __builtin_amdgcn_rcpf(1.0f + __expf(-x)); }
; template <int EPI>
; DI void epilogue(const Params& p, int layer, f32x16 (&acc)[2][2], int mrow0, int ncol0, int lane) {
;     ...
;   } else if (EPI == EPI_SWIGLU) {
;     bf16_t* G = (bf16_t*)(p.ws + OFF_U);
;     const int j = (ncol0 >> 7) * 64 + ((ncol0 >> 6) & 1) * 32 + c;
; #pragma unroll
;     for (int mi = 0; mi < 2; ++mi)
; #pragma unroll
;       for (int r = 0; r < 16; ++r) {
;         int row = mrow0 + mi * 32 + crow(r, h);
;         float a1 = acc[mi][0][r], a3 = acc[mi][1][r];
;         G[(size_t)row * FFH + j] = f2bf(silu_f(a1) * a3);
;       }
.Lmg_epi2:
	s_lshl_b32 s90, s78, 7
	s_add_u32 s90, s90, s67
	s_lshl_b32 s91, s79, 6
	s_add_u32 s91, s91, s68
	s_mov_b32 s82, s24
	s_mov_b32 s83, s25
	s_lshr_b32 s1, s68, 7
	s_lshl_b32 s1, s1, 1
	s_add_u32 s1, s1, s79
	s_mul_i32 s1, s1, 0x8800
	s_add_u32 s1, s1, s90
	v_lshl_add_u32 v184, v228, 2, s1
	v_lshlrev_b32_e32 v184, 6, v184
	v_lshl_add_u32 v229, v227, 1, v184
	v_mov_b32_e32 v148, v229
	v_mul_f32_e32 v144, 0xbfb8aa3b, v0
	v_mul_f32_e32 v145, 0xbfb8aa3b, v1
	v_mul_f32_e32 v146, 0xbfb8aa3b, v2
	v_mul_f32_e32 v147, 0xbfb8aa3b, v3
	v_exp_f32_e32 v144, v144
	v_exp_f32_e32 v145, v145
	v_exp_f32_e32 v146, v146
	v_exp_f32_e32 v147, v147
	s_nop 1
	v_add_f32_e32 v144, 1.0, v144
	v_add_f32_e32 v145, 1.0, v145
	v_add_f32_e32 v146, 1.0, v146
	v_add_f32_e32 v147, 1.0, v147
	v_rcp_f32_e32 v144, v144
	v_rcp_f32_e32 v145, v145
	v_rcp_f32_e32 v146, v146
	v_rcp_f32_e32 v147, v147
	s_nop 0
	v_mul_f32_e32 v144, v0, v144
	v_mul_f32_e32 v145, v1, v145
	v_mul_f32_e32 v146, v2, v146
	v_mul_f32_e32 v147, v3, v147
	v_mul_f32_e32 v144, v16, v144
	v_mul_f32_e32 v145, v17, v145
	v_mul_f32_e32 v146, v18, v146
	v_mul_f32_e32 v147, v19, v147
	v_cvt_pk_bf16_f32 v152, v144, v145
	v_cvt_pk_bf16_f32 v153, v146, v147
	global_store_short v148, v152, s[82:83] offset:0
	global_store_short_d16_hi v148, v152, s[82:83] offset:64
	global_store_short v148, v153, s[82:83] offset:128
	global_store_short_d16_hi v148, v153, s[82:83] offset:192
	v_mul_f32_e32 v144, 0xbfb8aa3b, v4
	v_mul_f32_e32 v145, 0xbfb8aa3b, v5
	v_mul_f32_e32 v146, 0xbfb8aa3b, v6
	v_mul_f32_e32 v147, 0xbfb8aa3b, v7
	v_exp_f32_e32 v144, v144
	v_exp_f32_e32 v145, v145
	v_exp_f32_e32 v146, v146
	v_exp_f32_e32 v147, v147
	s_nop 1
	v_add_f32_e32 v144, 1.0, v144
	v_add_f32_e32 v145, 1.0, v145
	v_add_f32_e32 v146, 1.0, v146
	v_add_f32_e32 v147, 1.0, v147
	v_rcp_f32_e32 v144, v144
	v_rcp_f32_e32 v145, v145
	v_rcp_f32_e32 v146, v146
	v_rcp_f32_e32 v147, v147
	s_nop 0
	v_mul_f32_e32 v144, v4, v144
	v_mul_f32_e32 v145, v5, v145
	v_mul_f32_e32 v146, v6, v146
	v_mul_f32_e32 v147, v7, v147
	v_mul_f32_e32 v144, v20, v144
	v_mul_f32_e32 v145, v21, v145
	v_mul_f32_e32 v146, v22, v146
	v_mul_f32_e32 v147, v23, v147
	v_cvt_pk_bf16_f32 v154, v144, v145
	v_cvt_pk_bf16_f32 v155, v146, v147
	global_store_short v148, v154, s[82:83] offset:512
	global_store_short_d16_hi v148, v154, s[82:83] offset:576
	global_store_short v148, v155, s[82:83] offset:640
	global_store_short_d16_hi v148, v155, s[82:83] offset:704
	v_mul_f32_e32 v144, 0xbfb8aa3b, v8
	v_mul_f32_e32 v145, 0xbfb8aa3b, v9
	v_mul_f32_e32 v146, 0xbfb8aa3b, v10
	v_mul_f32_e32 v147, 0xbfb8aa3b, v11
	v_exp_f32_e32 v144, v144
	v_exp_f32_e32 v145, v145
	v_exp_f32_e32 v146, v146
	v_exp_f32_e32 v147, v147
	s_nop 1
	v_add_f32_e32 v144, 1.0, v144
	v_add_f32_e32 v145, 1.0, v145
	v_add_f32_e32 v146, 1.0, v146
	v_add_f32_e32 v147, 1.0, v147
	v_rcp_f32_e32 v144, v144
	v_rcp_f32_e32 v145, v145
	v_rcp_f32_e32 v146, v146
	v_rcp_f32_e32 v147, v147
	s_nop 0
	v_mul_f32_e32 v144, v8, v144
	v_mul_f32_e32 v145, v9, v145
	v_mul_f32_e32 v146, v10, v146
	v_mul_f32_e32 v147, v11, v147
	v_mul_f32_e32 v144, v24, v144
	v_mul_f32_e32 v145, v25, v145
	v_mul_f32_e32 v146, v26, v146
	v_mul_f32_e32 v147, v27, v147
	v_cvt_pk_bf16_f32 v152, v144, v145
	v_cvt_pk_bf16_f32 v153, v146, v147
	global_store_short v148, v152, s[82:83] offset:1024
	global_store_short_d16_hi v148, v152, s[82:83] offset:1088
	global_store_short v148, v153, s[82:83] offset:1152
	global_store_short_d16_hi v148, v153, s[82:83] offset:1216
	v_mul_f32_e32 v144, 0xbfb8aa3b, v12
	v_mul_f32_e32 v145, 0xbfb8aa3b, v13
	v_mul_f32_e32 v146, 0xbfb8aa3b, v14
	v_mul_f32_e32 v147, 0xbfb8aa3b, v15
	v_exp_f32_e32 v144, v144
	v_exp_f32_e32 v145, v145
	v_exp_f32_e32 v146, v146
	v_exp_f32_e32 v147, v147
	s_nop 1
	v_add_f32_e32 v144, 1.0, v144
	v_add_f32_e32 v145, 1.0, v145
	v_add_f32_e32 v146, 1.0, v146
	v_add_f32_e32 v147, 1.0, v147
	v_rcp_f32_e32 v144, v144
	v_rcp_f32_e32 v145, v145
	v_rcp_f32_e32 v146, v146
	v_rcp_f32_e32 v147, v147
	s_nop 0
	v_mul_f32_e32 v144, v12, v144
	v_mul_f32_e32 v145, v13, v145
	v_mul_f32_e32 v146, v14, v146
	v_mul_f32_e32 v147, v15, v147
	v_mul_f32_e32 v144, v28, v144
	v_mul_f32_e32 v145, v29, v145
	v_mul_f32_e32 v146, v30, v146
	v_mul_f32_e32 v147, v31, v147
	v_cvt_pk_bf16_f32 v154, v144, v145
	v_cvt_pk_bf16_f32 v155, v146, v147
	global_store_short v148, v154, s[82:83] offset:1536
	global_store_short_d16_hi v148, v154, s[82:83] offset:1600
	global_store_short v148, v155, s[82:83] offset:1664
	global_store_short_d16_hi v148, v155, s[82:83] offset:1728
	v_add_u32_e32 v148, 0x800, v229
	v_mul_f32_e32 v144, 0xbfb8aa3b, v32
	v_mul_f32_e32 v145, 0xbfb8aa3b, v33
	v_mul_f32_e32 v146, 0xbfb8aa3b, v34
	v_mul_f32_e32 v147, 0xbfb8aa3b, v35
	v_exp_f32_e32 v144, v144
	v_exp_f32_e32 v145, v145
	v_exp_f32_e32 v146, v146
	v_exp_f32_e32 v147, v147
	s_nop 1
	v_add_f32_e32 v144, 1.0, v144
	v_add_f32_e32 v145, 1.0, v145
	v_add_f32_e32 v146, 1.0, v146
	v_add_f32_e32 v147, 1.0, v147
	v_rcp_f32_e32 v144, v144
	v_rcp_f32_e32 v145, v145
	v_rcp_f32_e32 v146, v146
	v_rcp_f32_e32 v147, v147
	s_nop 0
	v_mul_f32_e32 v144, v32, v144
	v_mul_f32_e32 v145, v33, v145
	v_mul_f32_e32 v146, v34, v146
	v_mul_f32_e32 v147, v35, v147
	v_mul_f32_e32 v144, v48, v144
	v_mul_f32_e32 v145, v49, v145
	v_mul_f32_e32 v146, v50, v146
	v_mul_f32_e32 v147, v51, v147
	v_cvt_pk_bf16_f32 v152, v144, v145
	v_cvt_pk_bf16_f32 v153, v146, v147
	global_store_short v148, v152, s[82:83] offset:0
	global_store_short_d16_hi v148, v152, s[82:83] offset:64
	global_store_short v148, v153, s[82:83] offset:128
	global_store_short_d16_hi v148, v153, s[82:83] offset:192
	v_mul_f32_e32 v144, 0xbfb8aa3b, v36
; DI bf16_t f2bf(float x) { return (bf16_t)(pack2(x, x) & 0xffffu); }
; DI int crow(int reg, int h) { return (reg & 3) + 8 * (reg >> 2) + 4 * h; }
; DI float silu_f(float x) { return x * __builtin_amdgcn_rcpf(1.0f + __expf(-x)); }
; template <int EPI>
; DI void epilogue(const Params& p, int layer, f32x16 (&acc)[2][2], int mrow0, int ncol0, int lane) {
;     ...
;   } else if (EPI == EPI_SWIGLU) {
;     bf16_t* G = (bf16_t*)(p.ws + OFF_U);
;     const int j = (ncol0 >> 7) * 64 + ((ncol0 >> 6) & 1) * 32 + c;
; #pragma unroll
;     for (int mi = 0; mi < 2; ++mi)
; #pragma unroll
;       for (int r = 0; r < 16; ++r) {
;         int row = mrow0 + mi * 32 + crow(r, h);
;         float a1 = acc[mi][0][r], a3 = acc[mi][1][r];
;         G[(size_t)row * FFH + j] = f2bf(silu_f(a1) * a3);
;       }
	v_mul_f32_e32 v145, 0xbfb8aa3b, v37
	v_mul_f32_e32 v146, 0xbfb8aa3b, v38
	v_mul_f32_e32 v147, 0xbfb8aa3b, v39
	v_exp_f32_e32 v144, v144
	v_exp_f32_e32 v145, v145
	v_exp_f32_e32 v146, v146
	v_exp_f32_e32 v147, v147
	s_nop 1
	v_add_f32_e32 v144, 1.0, v144
	v_add_f32_e32 v145, 1.0, v145
	v_add_f32_e32 v146, 1.0, v146
	v_add_f32_e32 v147, 1.0, v147
	v_rcp_f32_e32 v144, v144
	v_rcp_f32_e32 v145, v145
	v_rcp_f32_e32 v146, v146
	v_rcp_f32_e32 v147, v147
	s_nop 0
	v_mul_f32_e32 v144, v36, v144
	v_mul_f32_e32 v145, v37, v145
	v_mul_f32_e32 v146, v38, v146
	v_mul_f32_e32 v147, v39, v147
	v_mul_f32_e32 v144, v52, v144
	v_mul_f32_e32 v145, v53, v145
	v_mul_f32_e32 v146, v54, v146
	v_mul_f32_e32 v147, v55, v147
	v_cvt_pk_bf16_f32 v154, v144, v145
	v_cvt_pk_bf16_f32 v155, v146, v147
	global_store_short v148, v154, s[82:83] offset:512
	global_store_short_d16_hi v148, v154, s[82:83] offset:576
	global_store_short v148, v155, s[82:83] offset:640
	global_store_short_d16_hi v148, v155, s[82:83] offset:704
	v_mul_f32_e32 v144, 0xbfb8aa3b, v40
	v_mul_f32_e32 v145, 0xbfb8aa3b, v41
	v_mul_f32_e32 v146, 0xbfb8aa3b, v42
	v_mul_f32_e32 v147, 0xbfb8aa3b, v43
	v_exp_f32_e32 v144, v144
	v_exp_f32_e32 v145, v145
	v_exp_f32_e32 v146, v146
	v_exp_f32_e32 v147, v147
	s_nop 1
	v_add_f32_e32 v144, 1.0, v144
	v_add_f32_e32 v145, 1.0, v145
	v_add_f32_e32 v146, 1.0, v146
	v_add_f32_e32 v147, 1.0, v147
	v_rcp_f32_e32 v144, v144
	v_rcp_f32_e32 v145, v145
	v_rcp_f32_e32 v146, v146
	v_rcp_f32_e32 v147, v147
	s_nop 0
	v_mul_f32_e32 v144, v40, v144
	v_mul_f32_e32 v145, v41, v145
	v_mul_f32_e32 v146, v42, v146
	v_mul_f32_e32 v147, v43, v147
	v_mul_f32_e32 v144, v56, v144
	v_mul_f32_e32 v145, v57, v145
	v_mul_f32_e32 v146, v58, v146
	v_mul_f32_e32 v147, v59, v147
	v_cvt_pk_bf16_f32 v152, v144, v145
	v_cvt_pk_bf16_f32 v153, v146, v147
	global_store_short v148, v152, s[82:83] offset:1024
	global_store_short_d16_hi v148, v152, s[82:83] offset:1088
	global_store_short v148, v153, s[82:83] offset:1152
	global_store_short_d16_hi v148, v153, s[82:83] offset:1216
	v_mul_f32_e32 v144, 0xbfb8aa3b, v44
	v_mul_f32_e32 v145, 0xbfb8aa3b, v45
	v_mul_f32_e32 v146, 0xbfb8aa3b, v46
	v_mul_f32_e32 v147, 0xbfb8aa3b, v47
	v_exp_f32_e32 v144, v144
	v_exp_f32_e32 v145, v145
	v_exp_f32_e32 v146, v146
	v_exp_f32_e32 v147, v147
	s_nop 1
	v_add_f32_e32 v144, 1.0, v144
	v_add_f32_e32 v145, 1.0, v145
	v_add_f32_e32 v146, 1.0, v146
	v_add_f32_e32 v147, 1.0, v147
	v_rcp_f32_e32 v144, v144
	v_rcp_f32_e32 v145, v145
	v_rcp_f32_e32 v146, v146
	v_rcp_f32_e32 v147, v147
	s_nop 0
	v_mul_f32_e32 v144, v44, v144
	v_mul_f32_e32 v145, v45, v145
	v_mul_f32_e32 v146, v46, v146
	v_mul_f32_e32 v147, v47, v147
	v_mul_f32_e32 v144, v60, v144
	v_mul_f32_e32 v145, v61, v145
	v_mul_f32_e32 v146, v62, v146
	v_mul_f32_e32 v147, v63, v147
	v_cvt_pk_bf16_f32 v154, v144, v145
	v_cvt_pk_bf16_f32 v155, v146, v147
	global_store_short v148, v154, s[82:83] offset:1536
	global_store_short_d16_hi v148, v154, s[82:83] offset:1600
	global_store_short v148, v155, s[82:83] offset:1664
	global_store_short_d16_hi v148, v155, s[82:83] offset:1728
	v_add_u32_e32 v148, 0x1000, v229
	v_mul_f32_e32 v144, 0xbfb8aa3b, v64
	v_mul_f32_e32 v145, 0xbfb8aa3b, v65
	v_mul_f32_e32 v146, 0xbfb8aa3b, v66
	v_mul_f32_e32 v147, 0xbfb8aa3b, v67
	v_exp_f32_e32 v144, v144
	v_exp_f32_e32 v145, v145
	v_exp_f32_e32 v146, v146
	v_exp_f32_e32 v147, v147
	s_nop 1
	v_add_f32_e32 v144, 1.0, v144
	v_add_f32_e32 v145, 1.0, v145
	v_add_f32_e32 v146, 1.0, v146
	v_add_f32_e32 v147, 1.0, v147
	v_rcp_f32_e32 v144, v144
	v_rcp_f32_e32 v145, v145
	v_rcp_f32_e32 v146, v146
	v_rcp_f32_e32 v147, v147
	s_nop 0
	v_mul_f32_e32 v144, v64, v144
	v_mul_f32_e32 v145, v65, v145
	v_mul_f32_e32 v146, v66, v146
	v_mul_f32_e32 v147, v67, v147
	v_mul_f32_e32 v144, v80, v144
	v_mul_f32_e32 v145, v81, v145
	v_mul_f32_e32 v146, v82, v146
	v_mul_f32_e32 v147, v83, v147
	v_cvt_pk_bf16_f32 v152, v144, v145
	v_cvt_pk_bf16_f32 v153, v146, v147
	global_store_short v148, v152, s[82:83] offset:0
	global_store_short_d16_hi v148, v152, s[82:83] offset:64
	global_store_short v148, v153, s[82:83] offset:128
	global_store_short_d16_hi v148, v153, s[82:83] offset:192
	v_mul_f32_e32 v144, 0xbfb8aa3b, v68
	v_mul_f32_e32 v145, 0xbfb8aa3b, v69
	v_mul_f32_e32 v146, 0xbfb8aa3b, v70
	v_mul_f32_e32 v147, 0xbfb8aa3b, v71
	v_exp_f32_e32 v144, v144
	v_exp_f32_e32 v145, v145
	v_exp_f32_e32 v146, v146
	v_exp_f32_e32 v147, v147
	s_nop 1
	v_add_f32_e32 v144, 1.0, v144
	v_add_f32_e32 v145, 1.0, v145
	v_add_f32_e32 v146, 1.0, v146
	v_add_f32_e32 v147, 1.0, v147
	v_rcp_f32_e32 v144, v144
	v_rcp_f32_e32 v145, v145
	v_rcp_f32_e32 v146, v146
	v_rcp_f32_e32 v147, v147
	s_nop 0
	v_mul_f32_e32 v144, v68, v144
	v_mul_f32_e32 v145, v69, v145
	v_mul_f32_e32 v146, v70, v146
	v_mul_f32_e32 v147, v71, v147
	v_mul_f32_e32 v144, v84, v144
	v_mul_f32_e32 v145, v85, v145
	v_mul_f32_e32 v146, v86, v146
	v_mul_f32_e32 v147, v87, v147
	v_cvt_pk_bf16_f32 v154, v144, v145
	v_cvt_pk_bf16_f32 v155, v146, v147
	global_store_short v148, v154, s[82:83] offset:512
	global_store_short_d16_hi v148, v154, s[82:83] offset:576
	global_store_short v148, v155, s[82:83] offset:640
	global_store_short_d16_hi v148, v155, s[82:83] offset:704
	v_mul_f32_e32 v144, 0xbfb8aa3b, v72
	v_mul_f32_e32 v145, 0xbfb8aa3b, v73
	v_mul_f32_e32 v146, 0xbfb8aa3b, v74
	v_mul_f32_e32 v147, 0xbfb8aa3b, v75
	v_exp_f32_e32 v144, v144
	v_exp_f32_e32 v145, v145
	v_exp_f32_e32 v146, v146
	v_exp_f32_e32 v147, v147
	s_nop 1
	v_add_f32_e32 v144, 1.0, v144
	v_add_f32_e32 v145, 1.0, v145
	v_add_f32_e32 v146, 1.0, v146
	v_add_f32_e32 v147, 1.0, v147
	v_rcp_f32_e32 v144, v144
	v_rcp_f32_e32 v145, v145
; DI bf16_t f2bf(float x) { return (bf16_t)(pack2(x, x) & 0xffffu); }
; DI int crow(int reg, int h) { return (reg & 3) + 8 * (reg >> 2) + 4 * h; }
; DI float silu_f(float x) { return x * __builtin_amdgcn_rcpf(1.0f + __expf(-x)); }
; template <int EPI>
; DI void epilogue(const Params& p, int layer, f32x16 (&acc)[2][2], int mrow0, int ncol0, int lane) {
;     ...
;   } else if (EPI == EPI_SWIGLU) {
;     bf16_t* G = (bf16_t*)(p.ws + OFF_U);
;     const int j = (ncol0 >> 7) * 64 + ((ncol0 >> 6) & 1) * 32 + c;
; #pragma unroll
;     for (int mi = 0; mi < 2; ++mi)
; #pragma unroll
;       for (int r = 0; r < 16; ++r) {
;         int row = mrow0 + mi * 32 + crow(r, h);
;         float a1 = acc[mi][0][r], a3 = acc[mi][1][r];
;         G[(size_t)row * FFH + j] = f2bf(silu_f(a1) * a3);
;       }
	v_rcp_f32_e32 v146, v146
	v_rcp_f32_e32 v147, v147
	s_nop 0
	v_mul_f32_e32 v144, v72, v144
	v_mul_f32_e32 v145, v73, v145
	v_mul_f32_e32 v146, v74, v146
	v_mul_f32_e32 v147, v75, v147
	v_mul_f32_e32 v144, v88, v144
	v_mul_f32_e32 v145, v89, v145
	v_mul_f32_e32 v146, v90, v146
	v_mul_f32_e32 v147, v91, v147
	v_cvt_pk_bf16_f32 v152, v144, v145
	v_cvt_pk_bf16_f32 v153, v146, v147
	global_store_short v148, v152, s[82:83] offset:1024
	global_store_short_d16_hi v148, v152, s[82:83] offset:1088
	global_store_short v148, v153, s[82:83] offset:1152
	global_store_short_d16_hi v148, v153, s[82:83] offset:1216
	v_mul_f32_e32 v144, 0xbfb8aa3b, v76
	v_mul_f32_e32 v145, 0xbfb8aa3b, v77
	v_mul_f32_e32 v146, 0xbfb8aa3b, v78
	v_mul_f32_e32 v147, 0xbfb8aa3b, v79
	v_exp_f32_e32 v144, v144
	v_exp_f32_e32 v145, v145
	v_exp_f32_e32 v146, v146
	v_exp_f32_e32 v147, v147
	s_nop 1
	v_add_f32_e32 v144, 1.0, v144
	v_add_f32_e32 v145, 1.0, v145
	v_add_f32_e32 v146, 1.0, v146
	v_add_f32_e32 v147, 1.0, v147
	v_rcp_f32_e32 v144, v144
	v_rcp_f32_e32 v145, v145
	v_rcp_f32_e32 v146, v146
	v_rcp_f32_e32 v147, v147
	s_nop 0
	v_mul_f32_e32 v144, v76, v144
	v_mul_f32_e32 v145, v77, v145
	v_mul_f32_e32 v146, v78, v146
	v_mul_f32_e32 v147, v79, v147
	v_mul_f32_e32 v144, v92, v144
	v_mul_f32_e32 v145, v93, v145
	v_mul_f32_e32 v146, v94, v146
	v_mul_f32_e32 v147, v95, v147
	v_cvt_pk_bf16_f32 v154, v144, v145
	v_cvt_pk_bf16_f32 v155, v146, v147
	global_store_short v148, v154, s[82:83] offset:1536
	global_store_short_d16_hi v148, v154, s[82:83] offset:1600
	global_store_short v148, v155, s[82:83] offset:1664
	global_store_short_d16_hi v148, v155, s[82:83] offset:1728
	v_add_u32_e32 v148, 0x1800, v229
	v_mul_f32_e32 v144, 0xbfb8aa3b, v96
	v_mul_f32_e32 v145, 0xbfb8aa3b, v97
	v_mul_f32_e32 v146, 0xbfb8aa3b, v98
	v_mul_f32_e32 v147, 0xbfb8aa3b, v99
	v_exp_f32_e32 v144, v144
	v_exp_f32_e32 v145, v145
	v_exp_f32_e32 v146, v146
	v_exp_f32_e32 v147, v147
	s_nop 1
	v_add_f32_e32 v144, 1.0, v144
	v_add_f32_e32 v145, 1.0, v145
	v_add_f32_e32 v146, 1.0, v146
	v_add_f32_e32 v147, 1.0, v147
	v_rcp_f32_e32 v144, v144
	v_rcp_f32_e32 v145, v145
	v_rcp_f32_e32 v146, v146
	v_rcp_f32_e32 v147, v147
	s_nop 0
	v_mul_f32_e32 v144, v96, v144
	v_mul_f32_e32 v145, v97, v145
	v_mul_f32_e32 v146, v98, v146
	v_mul_f32_e32 v147, v99, v147
	v_mul_f32_e32 v144, v112, v144
	v_mul_f32_e32 v145, v113, v145
	v_mul_f32_e32 v146, v114, v146
	v_mul_f32_e32 v147, v115, v147
	v_cvt_pk_bf16_f32 v152, v144, v145
	v_cvt_pk_bf16_f32 v153, v146, v147
	global_store_short v148, v152, s[82:83] offset:0
	global_store_short_d16_hi v148, v152, s[82:83] offset:64
	global_store_short v148, v153, s[82:83] offset:128
	global_store_short_d16_hi v148, v153, s[82:83] offset:192
	v_mul_f32_e32 v144, 0xbfb8aa3b, v100
	v_mul_f32_e32 v145, 0xbfb8aa3b, v101
	v_mul_f32_e32 v146, 0xbfb8aa3b, v102
	v_mul_f32_e32 v147, 0xbfb8aa3b, v103
	v_exp_f32_e32 v144, v144
	v_exp_f32_e32 v145, v145
	v_exp_f32_e32 v146, v146
	v_exp_f32_e32 v147, v147
	s_nop 1
	v_add_f32_e32 v144, 1.0, v144
	v_add_f32_e32 v145, 1.0, v145
	v_add_f32_e32 v146, 1.0, v146
	v_add_f32_e32 v147, 1.0, v147
	v_rcp_f32_e32 v144, v144
	v_rcp_f32_e32 v145, v145
	v_rcp_f32_e32 v146, v146
	v_rcp_f32_e32 v147, v147
	s_nop 0
	v_mul_f32_e32 v144, v100, v144
	v_mul_f32_e32 v145, v101, v145
	v_mul_f32_e32 v146, v102, v146
	v_mul_f32_e32 v147, v103, v147
	v_mul_f32_e32 v144, v116, v144
	v_mul_f32_e32 v145, v117, v145
	v_mul_f32_e32 v146, v118, v146
	v_mul_f32_e32 v147, v119, v147
	v_cvt_pk_bf16_f32 v154, v144, v145
	v_cvt_pk_bf16_f32 v155, v146, v147
	global_store_short v148, v154, s[82:83] offset:512
	global_store_short_d16_hi v148, v154, s[82:83] offset:576
	global_store_short v148, v155, s[82:83] offset:640
	global_store_short_d16_hi v148, v155, s[82:83] offset:704
	v_mul_f32_e32 v144, 0xbfb8aa3b, v104
	v_mul_f32_e32 v145, 0xbfb8aa3b, v105
	v_mul_f32_e32 v146, 0xbfb8aa3b, v106
	v_mul_f32_e32 v147, 0xbfb8aa3b, v107
	v_exp_f32_e32 v144, v144
	v_exp_f32_e32 v145, v145
	v_exp_f32_e32 v146, v146
	v_exp_f32_e32 v147, v147
	s_nop 1
	v_add_f32_e32 v144, 1.0, v144
	v_add_f32_e32 v145, 1.0, v145
	v_add_f32_e32 v146, 1.0, v146
	v_add_f32_e32 v147, 1.0, v147
	v_rcp_f32_e32 v144, v144
	v_rcp_f32_e32 v145, v145
	v_rcp_f32_e32 v146, v146
	v_rcp_f32_e32 v147, v147
	s_nop 0
	v_mul_f32_e32 v144, v104, v144
	v_mul_f32_e32 v145, v105, v145
	v_mul_f32_e32 v146, v106, v146
	v_mul_f32_e32 v147, v107, v147
	v_mul_f32_e32 v144, v120, v144
	v_mul_f32_e32 v145, v121, v145
	v_mul_f32_e32 v146, v122, v146
	v_mul_f32_e32 v147, v123, v147
	v_cvt_pk_bf16_f32 v152, v144, v145
	v_cvt_pk_bf16_f32 v153, v146, v147
	global_store_short v148, v152, s[82:83] offset:1024
	global_store_short_d16_hi v148, v152, s[82:83] offset:1088
	global_store_short v148, v153, s[82:83] offset:1152
	global_store_short_d16_hi v148, v153, s[82:83] offset:1216
	v_mul_f32_e32 v144, 0xbfb8aa3b, v108
	v_mul_f32_e32 v145, 0xbfb8aa3b, v109
	v_mul_f32_e32 v146, 0xbfb8aa3b, v110
	v_mul_f32_e32 v147, 0xbfb8aa3b, v111
	v_exp_f32_e32 v144, v144
	v_exp_f32_e32 v145, v145
	v_exp_f32_e32 v146, v146
	v_exp_f32_e32 v147, v147
	s_nop 1
	v_add_f32_e32 v144, 1.0, v144
	v_add_f32_e32 v145, 1.0, v145
	v_add_f32_e32 v146, 1.0, v146
	v_add_f32_e32 v147, 1.0, v147
	v_rcp_f32_e32 v144, v144
	v_rcp_f32_e32 v145, v145
	v_rcp_f32_e32 v146, v146
	v_rcp_f32_e32 v147, v147
	s_nop 0
	v_mul_f32_e32 v144, v108, v144
	v_mul_f32_e32 v145, v109, v145
	v_mul_f32_e32 v146, v110, v146
	v_mul_f32_e32 v147, v111, v147
	v_mul_f32_e32 v144, v124, v144
	v_mul_f32_e32 v145, v125, v145
	v_mul_f32_e32 v146, v126, v146
	v_mul_f32_e32 v147, v127, v147
	v_cvt_pk_bf16_f32 v154, v144, v145
	v_cvt_pk_bf16_f32 v155, v146, v147
	global_store_short v148, v154, s[82:83] offset:1536
	global_store_short_d16_hi v148, v154, s[82:83] offset:1600
	global_store_short v148, v155, s[82:83] offset:1664
	global_store_short_d16_hi v148, v155, s[82:83] offset:1728
	s_branch .Lmg_next

; DI int get_tid() { int t = threadIdx.x; asm volatile("" : "+v"(t)); return t; }
; template <int DQK>
; DI void attn_item(const bf16_t* __restrict__ Q, const bf16_t* __restrict__ Kp, const bf16_t* __restrict__ Vt, int q0, int nkeys,
;                   bf16_t* __restrict__ mix, int colbase, int b, char* smem) {
;     ...
;   const int tid = get_tid(), lane = tid & 63, wave = tid >> 6, r = lane & 31, h = lane >> 5;
;   bf16x8 qf[NSTEP];
;   {
;     const bf16_t* qr = Q + (size_t)(q0 + wave * 32 + r) * DQK + 8 * h;
; #pragma unroll
;     for (int s = 0; s < NSTEP; ++s) qf[s] = *(const bf16x8*)(qr + 16 * s);
;   }
;   const int kid0 = tid, kid1 = tid + 256, kid2 = tid + 512;
;   const int kgo0 = (kid0 / KCH) * DQK + (kid0 % KCH) * 8, kgo1 = (kid1 / KCH) * DQK + (kid1 % KCH) * 8, kgo2 = (kid2 / KCH) * DQK + (kid2 % KCH) * 8;
;   const int kso0 = (kid0 / KCH) * KROW + (kid0 % KCH) * 8, kso1 = (kid1 / KCH) * KROW + (kid1 % KCH) * 8, kso2 = (kid2 / KCH) * KROW + (kid2 % KCH) * 8;
;   const int vrow0 = tid >> 3, vcc = (tid & 7) * 8;
;   const bf16_t* Vg0 = Vt + (size_t)vrow0 * NKEY + vcc;
;   const bf16_t* Vg1 = Vt + (size_t)(vrow0 + 32) * NKEY + vcc;
;   const int vso0 = vrow0 * VROW + vcc, vso1 = (vrow0 + 32) * VROW + vcc;
; DI void phase_attn(const Params& p, int layer, char* smem) {
;   const int n_lat = 96 * 32, n_ctx = (layer == 0) ? 96 * 2 : 0;
;   for (int it = blockIdx.x; it < n_lat + n_ctx; it += gridDim.x) {
;     int combo, qb;
;     if (it < n_lat) { int xc = it & 7, j = it >> 3; combo = (j >> 5) * 8 + xc; qb = 2 + (j & 31); }
;     else { int r = it - n_lat; combo = r >> 1; qb = r & 1; }
;     const int type = combo / 48, bh = combo % 48;
;     attn_dispatch(p, type, bh / 6, bh % 6, qb, smem);
.Lmg_done:
	s_setprio 0
	s_mov_b32 s100, s52
	v_readlane_b32 s52, v254, 0
	v_readlane_b32 s53, v254, 1
	v_readlane_b32 s54, v254, 2
	v_readlane_b32 s55, v254, 3
	v_readlane_b32 s56, v254, 4
	v_readlane_b32 s57, v254, 5
	v_readlane_b32 s58, v254, 6
	v_readlane_b32 s59, v254, 7
	v_readlane_b32 s60, v254, 8
	v_readlane_b32 s61, v254, 9
	v_readlane_b32 s62, v254, 10
	v_readlane_b32 s63, v254, 11
	v_readlane_b32 s64, v254, 12
	v_readlane_b32 s65, v254, 13
	v_readlane_b32 s66, v254, 14
	v_readlane_b32 s67, v254, 15
	v_readlane_b32 s68, v254, 16
	v_readlane_b32 s69, v254, 17
	v_readlane_b32 s70, v254, 18
	v_readlane_b32 s71, v254, 19
	v_readlane_b32 s72, v254, 20
	v_readlane_b32 s73, v254, 21
	v_readlane_b32 s74, v254, 22
	v_readlane_b32 s75, v254, 23
	v_readlane_b32 s76, v254, 24
	v_readlane_b32 s77, v254, 25
	v_readlane_b32 s78, v254, 26
	v_readlane_b32 s79, v254, 27
	v_readlane_b32 s80, v254, 28
	v_readlane_b32 s81, v254, 29
	v_readlane_b32 s82, v254, 30
	v_readlane_b32 s83, v254, 31
	v_readlane_b32 s84, v254, 32
	v_readlane_b32 s85, v254, 33
	v_readlane_b32 s86, v254, 34
	v_readlane_b32 s87, v254, 35
	v_readlane_b32 s88, v254, 36
	v_readlane_b32 s89, v254, 37
	v_readlane_b32 s90, v254, 38
	v_readlane_b32 s91, v254, 39
	s_nop 3
	s_cmp_eq_u32 s100, 1
	s_cbranch_scc1 .LBB0_1546
	s_cmp_eq_u32 s100, 2
	s_cbranch_scc1 .LBB0_1650
	s_cmp_eq_u32 s100, 3
	s_cbranch_scc1 .LBB0_1711
	s_branch .LBB0_458
.Lat_entry:
	v_writelane_b32 v254, s52, 0
	v_writelane_b32 v254, s53, 1
	v_writelane_b32 v254, s54, 2
	v_writelane_b32 v254, s55, 3
	v_writelane_b32 v254, s56, 4
	v_writelane_b32 v254, s57, 5
	v_writelane_b32 v254, s58, 6
	v_writelane_b32 v254, s59, 7
	v_writelane_b32 v254, s60, 8
	v_writelane_b32 v254, s61, 9
	v_writelane_b32 v254, s62, 10
	v_writelane_b32 v254, s63, 11
	v_writelane_b32 v254, s64, 12
	v_writelane_b32 v254, s65, 13
	v_writelane_b32 v254, s66, 14
	v_writelane_b32 v254, s67, 15
	v_writelane_b32 v254, s68, 16
	v_writelane_b32 v254, s69, 17
	v_writelane_b32 v254, s70, 18
	v_writelane_b32 v254, s71, 19
	v_writelane_b32 v254, s72, 20
	v_writelane_b32 v254, s73, 21
	v_writelane_b32 v254, s74, 22
	v_writelane_b32 v254, s75, 23
	v_writelane_b32 v254, s76, 24
	v_writelane_b32 v254, s77, 25
	v_writelane_b32 v254, s78, 26
	v_writelane_b32 v254, s79, 27
	v_writelane_b32 v254, s80, 28
	v_writelane_b32 v254, s81, 29
	v_writelane_b32 v254, s82, 30
	v_writelane_b32 v254, s83, 31
	v_writelane_b32 v254, s84, 32
	v_writelane_b32 v254, s85, 33
	v_writelane_b32 v254, s86, 34
	v_writelane_b32 v254, s87, 35
	v_writelane_b32 v254, s88, 36
	v_writelane_b32 v254, s89, 37
	v_writelane_b32 v254, s90, 38
	v_writelane_b32 v254, s91, 39
	v_readlane_b32 s52, v255, 0
	v_and_b32_e32 v253, 31, v143
	v_lshrrev_b32_e32 v223, 6, v143
	v_bfe_u32 v140, v143, 5, 1
	s_nop 0
	v_readfirstlane_b32 s57, v223
	s_mov_b32 s72, s24
	s_mov_b32 s73, s25
	s_nop 3
.Lat_item:
	s_cmp_lt_u32 s52, 0xc00
	s_cbranch_scc0 .Lat_done
	s_and_b32 s0, s52, 7
	s_lshr_b32 s1, s52, 3
	s_lshr_b32 s10, s1, 5
	s_lshl_b32 s10, s10, 3
	s_add_u32 s10, s10, s0
	s_and_b32 s1, s1, 31
	s_add_u32 s1, s1, 2
	s_lshl_b32 s56, s1, 7
	s_mov_b32 s53, 0
	s_cmp_ge_u32 s10, 48
	s_cbranch_scc0 .Lat_ty_1
	s_mov_b32 s53, 1
	s_sub_u32 s10, s10, 48
.Lat_ty_1:
	s_mul_i32 s54, s10, 43
	s_lshr_b32 s54, s54, 8
	s_mul_i32 s11, s54, 6
	s_sub_u32 s55, s10, s11
	s_lshl_b32 s11, s54, 12
	s_add_u32 s11, s11, s56
	s_sub_u32 s11, s11, 256
	s_lshl_b32 s28, s57, 5
	s_add_u32 s11, s11, s28
	v_add_u32_e32 v252, s11, v253
	v_lshlrev_b32_e32 v252, 11, v252
	v_lshl_add_u32 v252, v140, 3, v252
	s_cmp_eq_u32 s53, 1
	s_cbranch_scc1 .Lat_mla_2
	s_mul_i32 s11, s54, 6
	s_add_u32 s11, s11, s55
	s_mul_i32 s28, s11, 0x88000
	s_add_u32 s28, s28, 0x7f80000
	s_add_u32 s58, s24, s28
	s_addc_u32 s59, s25, 0
	s_mul_i32 s29, s55, 43
	s_lshr_b32 s29, s29, 7
	s_lshl_b32 s11, s54, 1
	s_add_u32 s11, s11, s29
	s_mul_i32 s28, s11, 0x88000
	s_add_u32 s28, s28, 0x9900000
	s_add_u32 s60, s24, s28
	s_addc_u32 s61, s25, 0
	s_mul_i32 s28, s11, 0x88000
	s_add_u32 s28, s28, 0xa180000
	s_add_u32 s62, s24, s28
	s_addc_u32 s63, s25, 0
	s_lshl_b32 s28, s55, 7
	s_add_u32 s28, s28, 0x200
	v_add_u32_e32 v252, s28, v252
	s_lshl_b32 s28, s57, 5
	s_add_u32 s28, s28, s56
	v_add_u32_e32 v251, s28, v253
	s_movk_i32 s29, 128
	v_mul_lo_u32 v251, v251, s29
	v_lshl_add_u32 v251, v140, 4, v251
	s_movk_i32 s29, 144
	v_mul_lo_u32 v238, v253, s29
	v_lshl_add_u32 v238, v140, 4, v238
	s_movk_i32 s29, 136
	v_mul_lo_u32 v239, v253, s29
	v_lshl_add_u32 v239, v140, 3, v239
	v_add_u32_e32 v240, 0x1100, v239
	v_mov_b32_e32 v225, v143
	v_lshrrev_b32_e32 v226, 3, v225
	v_and_b32_e32 v227, 7, v225
	s_movk_i32 s29, 128
	v_mul_lo_u32 v246, v226, s29
	v_lshl_add_u32 v246, v227, 4, v246
	s_movk_i32 s29, 144
	v_mul_lo_u32 v241, v226, s29
	v_lshl_add_u32 v241, v227, 4, v241
	v_add_u32_e32 v225, 256, v143
	v_lshrrev_b32_e32 v226, 3, v225
	v_and_b32_e32 v227, 7, v225
	s_movk_i32 s29, 128
	v_mul_lo_u32 v247, v226, s29
	v_lshl_add_u32 v247, v227, 4, v247
	s_movk_i32 s29, 144
	v_mul_lo_u32 v242, v226, s29
	v_lshl_add_u32 v242, v227, 4, v242
	v_lshrrev_b32_e32 v226, 3, v143
	v_and_b32_e32 v227, 7, v143
	s_movk_i32 s29, 8704
	v_mul_lo_u32 v249, v226, s29
	v_lshl_add_u32 v249, v227, 4, v249
	v_add_u32_e32 v250, 0x44000, v249
	s_movk_i32 s29, 136
	v_mul_lo_u32 v244, v226, s29
	v_lshl_add_u32 v244, v227, 4, v244
	v_add_u32_e32 v245, 0x1100, v244
	s_barrier
; template <int DQK>
; DI void attn_item(const bf16_t* __restrict__ Q, const bf16_t* __restrict__ Kp, const bf16_t* __restrict__ Vt, int q0, int nkeys,
;                   bf16_t* __restrict__ mix, int colbase, int b, char* smem) {
;     ...
;   f32x16 o0, o1;
; #pragma unroll
;   for (int i = 0; i < 16; ++i) { o0[i] = 0.f; o1[i] = 0.f; }
;   float m = -1e30f, l = 0.f;
;     ...
;   const int nt = nkeys >> 6;
;   A_LOAD(p, 0)
;   A_LOAD(q, 64)
;   A_WRITE(p, 0)
;   __syncthreads();
;   if (nt > 2) A_LOAD(p, 128)
;   for (int kt = 0; kt < nt; kt += 2) {
	global_load_dwordx4 v[112:115], v251, s[58:59] offset:0
	global_load_dwordx4 v[116:119], v251, s[58:59] offset:32
	global_load_dwordx4 v[120:123], v251, s[58:59] offset:64
	global_load_dwordx4 v[124:127], v251, s[58:59] offset:96
	s_mov_b32 s1, 0
	s_min_u32 s0, s1, 67
	s_mul_i32 s0, s0, 0x2000
	s_add_u32 s64, s60, s0
	s_addc_u32 s65, s61, 0
	s_min_u32 s0, s1, 67
	s_lshl_b32 s0, s0, 7
	s_add_u32 s66, s62, s0
	s_addc_u32 s67, s63, 0
	global_load_dwordx4 v[176:179], v246, s[64:65]
	global_load_dwordx4 v[180:183], v247, s[64:65]
	global_load_dwordx4 v[212:215], v249, s[66:67]
	global_load_dwordx4 v[216:219], v250, s[66:67]
	s_waitcnt vmcnt(0)
	ds_write_b128 v241, v[176:179] offset:0
	ds_write_b128 v242, v[180:183] offset:0
	ds_write_b64 v244, v[212:213] offset:18432
	ds_write_b64 v244, v[214:215] offset:18440
	ds_write_b64 v245, v[216:217] offset:18432
	ds_write_b64 v245, v[218:219] offset:18440
	s_mov_b32 s1, 1
	s_min_u32 s0, s1, 67
	s_mul_i32 s0, s0, 0x2000
	s_add_u32 s64, s60, s0
	s_addc_u32 s65, s61, 0
	s_min_u32 s0, s1, 67
	s_lshl_b32 s0, s0, 7
	s_add_u32 s66, s62, s0
	s_addc_u32 s67, s63, 0
	global_load_dwordx4 v[176:179], v246, s[64:65]
	global_load_dwordx4 v[180:183], v247, s[64:65]
	s_waitcnt vmcnt(0)
	ds_write_b128 v241, v[176:179] offset:9216
	ds_write_b128 v242, v[180:183] offset:9216
	s_mov_b32 s1, 2
	s_mov_b32 s10, 1
	s_min_u32 s0, s1, 67
	s_mul_i32 s0, s0, 0x2000
	s_add_u32 s64, s60, s0
	s_addc_u32 s65, s61, 0
	s_min_u32 s0, s10, 67
	s_lshl_b32 s0, s0, 7
	s_add_u32 s66, s62, s0
	s_addc_u32 s67, s63, 0
	global_load_dwordx4 v[176:179], v246, s[64:65]
	global_load_dwordx4 v[180:183], v247, s[64:65]
	global_load_dwordx4 v[212:215], v249, s[66:67]
	global_load_dwordx4 v[216:219], v250, s[66:67]
	v_mov_b32_e32 v0, 0
	v_mov_b32_e32 v1, 0
	v_mov_b32_e32 v2, 0
	v_mov_b32_e32 v3, 0
	v_mov_b32_e32 v4, 0
	v_mov_b32_e32 v5, 0
	v_mov_b32_e32 v6, 0
	v_mov_b32_e32 v7, 0
	v_mov_b32_e32 v8, 0
	v_mov_b32_e32 v9, 0
	v_mov_b32_e32 v10, 0
	v_mov_b32_e32 v11, 0
	v_mov_b32_e32 v12, 0
	v_mov_b32_e32 v13, 0
	v_mov_b32_e32 v14, 0
	v_mov_b32_e32 v15, 0
	v_mov_b32_e32 v16, 0
	v_mov_b32_e32 v17, 0
	v_mov_b32_e32 v18, 0
	v_mov_b32_e32 v19, 0
	v_mov_b32_e32 v20, 0
	v_mov_b32_e32 v21, 0
	v_mov_b32_e32 v22, 0
	v_mov_b32_e32 v23, 0
	v_mov_b32_e32 v24, 0
	v_mov_b32_e32 v25, 0
	v_mov_b32_e32 v26, 0
	v_mov_b32_e32 v27, 0
	v_mov_b32_e32 v28, 0
	v_mov_b32_e32 v29, 0
	v_mov_b32_e32 v30, 0
	v_mov_b32_e32 v31, 0
	v_mov_b32_e32 v220, 0xf149f2ca
	v_mov_b32_e32 v221, 0
	s_waitcnt lgkmcnt(0)
	s_barrier
	ds_read_b128 v[144:147], v238 offset:0
	ds_read_b128 v[148:151], v238 offset:4608
	ds_read_b128 v[152:155], v238 offset:32
	ds_read_b128 v[156:159], v238 offset:4640
	s_waitcnt lgkmcnt(3)
	v_mfma_f32_32x32x16_bf16 v[32:47], v[144:147], v[112:115], 0
	ds_read_b128 v[144:147], v238 offset:64
	s_waitcnt lgkmcnt(3)
	v_mfma_f32_32x32x16_bf16 v[48:63], v[148:151], v[112:115], 0
	ds_read_b128 v[148:151], v238 offset:4672
	s_waitcnt lgkmcnt(3)
	v_mfma_f32_32x32x16_bf16 v[32:47], v[152:155], v[116:119], v[32:47]
	ds_read_b128 v[152:155], v238 offset:96
	s_waitcnt lgkmcnt(3)
	v_mfma_f32_32x32x16_bf16 v[48:63], v[156:159], v[116:119], v[48:63]
	ds_read_b128 v[156:159], v238 offset:4704
	s_waitcnt lgkmcnt(3)
	v_mfma_f32_32x32x16_bf16 v[32:47], v[144:147], v[120:123], v[32:47]
	s_waitcnt lgkmcnt(2)
	v_mfma_f32_32x32x16_bf16 v[48:63], v[148:151], v[120:123], v[48:63]
	s_waitcnt lgkmcnt(1)
	v_mfma_f32_32x32x16_bf16 v[32:47], v[152:155], v[124:127], v[32:47]
	s_waitcnt lgkmcnt(0)
	v_mfma_f32_32x32x16_bf16 v[48:63], v[156:159], v[124:127], v[48:63]
	s_waitcnt lgkmcnt(0)
	s_barrier
	s_mov_b32 s68, 0
.Lat_loop_g:
	s_waitcnt vmcnt(0)
	ds_write_b128 v241, v[176:179] offset:0
	ds_write_b128 v242, v[180:183] offset:0
	ds_write_b64 v244, v[212:213] offset:27136
	ds_write_b64 v244, v[214:215] offset:27144
	ds_write_b64 v245, v[216:217] offset:27136
	ds_write_b64 v245, v[218:219] offset:27144
	s_add_u32 s1, s68, 3
	s_add_u32 s10, s68, 2
	s_min_u32 s0, s1, 67
	s_mul_i32 s0, s0, 0x2000
	s_add_u32 s64, s60, s0
	s_addc_u32 s65, s61, 0
	s_min_u32 s0, s10, 67
	s_lshl_b32 s0, s0, 7
	s_add_u32 s66, s62, s0
	s_addc_u32 s67, s63, 0
	global_load_dwordx4 v[176:179], v246, s[64:65]
	global_load_dwordx4 v[180:183], v247, s[64:65]
	global_load_dwordx4 v[212:215], v249, s[66:67]
	global_load_dwordx4 v[216:219], v250, s[66:67]
	ds_read_b128 v[144:147], v238 offset:9216
	ds_read_b128 v[148:151], v238 offset:13824
	ds_read_b128 v[152:155], v238 offset:9248
	ds_read_b128 v[156:159], v238 offset:13856
	v_max3_f32 v223, v32, v33, v34
	v_max3_f32 v224, v40, v41, v42
	v_max3_f32 v225, v48, v49, v50
	v_max3_f32 v226, v56, v57, v58
	v_max3_f32 v223, v223, v35, v36
	v_max3_f32 v224, v224, v43, v44
	v_max3_f32 v225, v225, v51, v52
	v_max3_f32 v226, v226, v59, v60
	v_max3_f32 v223, v223, v37, v38
	s_waitcnt lgkmcnt(3)
	v_mfma_f32_32x32x16_bf16 v[64:79], v[144:147], v[112:115], 0
	ds_read_b128 v[144:147], v238 offset:9280
	v_max3_f32 v224, v224, v45, v46
	v_max3_f32 v225, v225, v53, v54
	v_max3_f32 v226, v226, v61, v62
	v_max_f32_e32 v223, v223, v39
	v_max_f32_e32 v224, v224, v47
	v_max_f32_e32 v225, v225, v55
	v_max_f32_e32 v226, v226, v63
	v_max3_f32 v222, v223, v224, v225
	v_max_f32_e32 v222, v222, v226
	s_waitcnt lgkmcnt(3)
	v_mfma_f32_32x32x16_bf16 v[80:95], v[148:151], v[112:115], 0
	ds_read_b128 v[148:151], v238 offset:13888
	v_mov_b32_e32 v227, v222
	v_add_f32_e32 v228, 0x41000000, v220
	s_nop 0
	v_permlane32_swap_b32_e32 v222, v227
	v_max_f32_e32 v222, v222, v227
	v_cmp_gt_f32_e32 vcc, v222, v228
	s_cbranch_vccz .Lat_nors_4
	v_max_f32_e32 v229, v220, v222
	v_sub_f32_e32 v230, v220, v229
	v_exp_f32_e32 v230, v230
	v_mov_b32_e32 v220, v229
	s_nop 0
	v_mul_f32_e32 v221, v221, v230
	v_mul_f32_e32 v0, v0, v230
	v_mul_f32_e32 v1, v1, v230
	v_mul_f32_e32 v2, v2, v230
	v_mul_f32_e32 v3, v3, v230
	v_mul_f32_e32 v4, v4, v230
	v_mul_f32_e32 v5, v5, v230
	v_mul_f32_e32 v6, v6, v230
	v_mul_f32_e32 v7, v7, v230
	v_mul_f32_e32 v8, v8, v230
	v_mul_f32_e32 v9, v9, v230
	v_mul_f32_e32 v10, v10, v230
	v_mul_f32_e32 v11, v11, v230
	v_mul_f32_e32 v12, v12, v230
	v_mul_f32_e32 v13, v13, v230
	v_mul_f32_e32 v14, v14, v230
	v_mul_f32_e32 v15, v15, v230
	v_mul_f32_e32 v16, v16, v230
	v_mul_f32_e32 v17, v17, v230
	v_mul_f32_e32 v18, v18, v230
	v_mul_f32_e32 v19, v19, v230
	v_mul_f32_e32 v20, v20, v230
	v_mul_f32_e32 v21, v21, v230
	v_mul_f32_e32 v22, v22, v230
	v_mul_f32_e32 v23, v23, v230
	v_mul_f32_e32 v24, v24, v230
	v_mul_f32_e32 v25, v25, v230
	v_mul_f32_e32 v26, v26, v230
	v_mul_f32_e32 v27, v27, v230
	v_mul_f32_e32 v28, v28, v230
	v_mul_f32_e32 v29, v29, v230
	v_mul_f32_e32 v30, v30, v230
	v_mul_f32_e32 v31, v31, v230
.Lat_nors_4:
	v_sub_f32_e32 v32, v32, v220
	v_sub_f32_e32 v33, v33, v220
	v_sub_f32_e32 v34, v34, v220
	s_waitcnt lgkmcnt(3)
	v_mfma_f32_32x32x16_bf16 v[64:79], v[152:155], v[116:119], v[64:79]
	ds_read_b128 v[152:155], v238 offset:9312
	v_sub_f32_e32 v35, v35, v220
	v_sub_f32_e32 v36, v36, v220
	v_sub_f32_e32 v37, v37, v220
	v_sub_f32_e32 v38, v38, v220
	v_sub_f32_e32 v39, v39, v220
	v_sub_f32_e32 v40, v40, v220
	v_sub_f32_e32 v41, v41, v220
	v_sub_f32_e32 v42, v42, v220
	v_sub_f32_e32 v43, v43, v220
	s_waitcnt lgkmcnt(3)
	v_mfma_f32_32x32x16_bf16 v[80:95], v[156:159], v[116:119], v[80:95]
	ds_read_b128 v[156:159], v238 offset:13920
	v_sub_f32_e32 v44, v44, v220
	v_sub_f32_e32 v45, v45, v220
	v_sub_f32_e32 v46, v46, v220
	v_sub_f32_e32 v47, v47, v220
	v_sub_f32_e32 v48, v48, v220
	v_sub_f32_e32 v49, v49, v220
	v_sub_f32_e32 v50, v50, v220
	v_sub_f32_e32 v51, v51, v220
	v_sub_f32_e32 v52, v52, v220
	s_waitcnt lgkmcnt(3)
	v_mfma_f32_32x32x16_bf16 v[64:79], v[144:147], v[120:123], v[64:79]
	v_sub_f32_e32 v53, v53, v220
	v_sub_f32_e32 v54, v54, v220
	v_sub_f32_e32 v55, v55, v220
	v_sub_f32_e32 v56, v56, v220
	v_sub_f32_e32 v57, v57, v220
	v_sub_f32_e32 v58, v58, v220
	v_sub_f32_e32 v59, v59, v220
	v_sub_f32_e32 v60, v60, v220
	v_sub_f32_e32 v61, v61, v220
	s_waitcnt lgkmcnt(2)
	v_mfma_f32_32x32x16_bf16 v[80:95], v[148:151], v[120:123], v[80:95]
	v_sub_f32_e32 v62, v62, v220
	v_sub_f32_e32 v63, v63, v220
	v_exp_f32_e32 v32, v32
	v_exp_f32_e32 v33, v33
	v_exp_f32_e32 v34, v34
	v_exp_f32_e32 v35, v35
	v_exp_f32_e32 v36, v36
	v_exp_f32_e32 v37, v37
	v_exp_f32_e32 v38, v38
	s_waitcnt lgkmcnt(1)
	v_mfma_f32_32x32x16_bf16 v[64:79], v[152:155], v[124:127], v[64:79]
	v_exp_f32_e32 v39, v39
	v_exp_f32_e32 v40, v40
	v_exp_f32_e32 v41, v41
	v_exp_f32_e32 v42, v42
	v_exp_f32_e32 v43, v43
	v_exp_f32_e32 v44, v44
	v_exp_f32_e32 v45, v45
	v_exp_f32_e32 v46, v46
	v_exp_f32_e32 v47, v47
	s_waitcnt lgkmcnt(0)
	v_mfma_f32_32x32x16_bf16 v[80:95], v[156:159], v[124:127], v[80:95]
	v_exp_f32_e32 v48, v48
	v_exp_f32_e32 v49, v49
	v_exp_f32_e32 v50, v50
	v_exp_f32_e32 v51, v51
	v_exp_f32_e32 v52, v52
	v_exp_f32_e32 v53, v53
	v_exp_f32_e32 v54, v54
	v_exp_f32_e32 v55, v55
	v_exp_f32_e32 v56, v56
	v_exp_f32_e32 v57, v57
	v_exp_f32_e32 v58, v58
	v_exp_f32_e32 v59, v59
	v_exp_f32_e32 v60, v60
	v_exp_f32_e32 v61, v61
	v_exp_f32_e32 v62, v62
	v_exp_f32_e32 v63, v63
	v_add_u32_e32 v223, 0x4800, v239
	v_add_u32_e32 v224, 0x4800, v240
	ds_read2_b64 v[160:163], v223 offset0:0 offset1:2
	ds_read2_b64 v[164:167], v224 offset0:0 offset1:2
	ds_read2_b64 v[168:171], v223 offset0:4 offset1:6
	ds_read2_b64 v[172:175], v224 offset0:4 offset1:6
	v_cvt_pk_bf16_f32 v96, v32, v33
	v_cvt_pk_bf16_f32 v97, v34, v35
	v_cvt_pk_bf16_f32 v98, v36, v37
	v_cvt_pk_bf16_f32 v99, v38, v39
	v_add_f32_e32 v231, v32, v36
	v_add_f32_e32 v232, v33, v37
	v_add_f32_e32 v233, v34, v38
	v_add_f32_e32 v237, v35, v39
	s_waitcnt lgkmcnt(3)
	v_mfma_f32_32x32x16_bf16 v[0:15], v[160:163], v[96:99], v[0:15]
	ds_read2_b64 v[160:163], v223 offset0:8 offset1:10
	s_waitcnt lgkmcnt(3)
	v_mfma_f32_32x32x16_bf16 v[16:31], v[164:167], v[96:99], v[16:31]
	ds_read2_b64 v[164:167], v224 offset0:8 offset1:10
	v_cvt_pk_bf16_f32 v100, v40, v41
	v_cvt_pk_bf16_f32 v101, v42, v43
	v_cvt_pk_bf16_f32 v102, v44, v45
	v_cvt_pk_bf16_f32 v103, v46, v47
	v_add_f32_e32 v231, v231, v40
	v_add_f32_e32 v232, v232, v41
	v_add_f32_e32 v233, v233, v42
	v_add_f32_e32 v237, v237, v43
	v_add_f32_e32 v231, v231, v44
	v_add_f32_e32 v232, v232, v45
	v_add_f32_e32 v233, v233, v46
	v_add_f32_e32 v237, v237, v47
	s_waitcnt lgkmcnt(3)
	v_mfma_f32_32x32x16_bf16 v[0:15], v[168:171], v[100:103], v[0:15]
	ds_read2_b64 v[168:171], v223 offset0:12 offset1:14
	s_waitcnt lgkmcnt(3)
	v_mfma_f32_32x32x16_bf16 v[16:31], v[172:175], v[100:103], v[16:31]
	ds_read2_b64 v[172:175], v224 offset0:12 offset1:14
	v_cvt_pk_bf16_f32 v104, v48, v49
	v_cvt_pk_bf16_f32 v105, v50, v51
	v_cvt_pk_bf16_f32 v106, v52, v53
	v_cvt_pk_bf16_f32 v107, v54, v55
	v_add_f32_e32 v231, v231, v48
	v_add_f32_e32 v232, v232, v49
	v_add_f32_e32 v233, v233, v50
	v_add_f32_e32 v237, v237, v51
	v_add_f32_e32 v231, v231, v52
	v_add_f32_e32 v232, v232, v53
	v_add_f32_e32 v233, v233, v54
	v_add_f32_e32 v237, v237, v55
	s_waitcnt lgkmcnt(3)
	v_mfma_f32_32x32x16_bf16 v[0:15], v[160:163], v[104:107], v[0:15]
	s_waitcnt lgkmcnt(2)
	v_mfma_f32_32x32x16_bf16 v[16:31], v[164:167], v[104:107], v[16:31]
	v_cvt_pk_bf16_f32 v108, v56, v57
	v_cvt_pk_bf16_f32 v109, v58, v59
	v_cvt_pk_bf16_f32 v110, v60, v61
	v_cvt_pk_bf16_f32 v111, v62, v63
	v_add_f32_e32 v231, v231, v56
	v_add_f32_e32 v232, v232, v57
	v_add_f32_e32 v233, v233, v58
	v_add_f32_e32 v237, v237, v59
	v_add_f32_e32 v231, v231, v60
	v_add_f32_e32 v232, v232, v61
	v_add_f32_e32 v233, v233, v62
	v_add_f32_e32 v237, v237, v63
	s_waitcnt lgkmcnt(1)
	v_mfma_f32_32x32x16_bf16 v[0:15], v[168:171], v[108:111], v[0:15]
	s_waitcnt lgkmcnt(0)
	v_mfma_f32_32x32x16_bf16 v[16:31], v[172:175], v[108:111], v[16:31]
	v_add_f32_e32 v231, v231, v232
	v_add_f32_e32 v233, v233, v237
	v_add_f32_e32 v231, v231, v233
	v_add_f32_e32 v221, v221, v231
	s_add_u32 s68, s68, 1
	s_waitcnt lgkmcnt(0)
	s_barrier
; template <int DQK>
; DI void attn_item(const bf16_t* __restrict__ Q, const bf16_t* __restrict__ Kp, const bf16_t* __restrict__ Vt, int q0, int nkeys,
;                   bf16_t* __restrict__ mix, int colbase, int b, char* smem) {
;     ...
;   for (int kt = 0; kt < nt; kt += 2) {
;     A_TILE(0)
;     A_WRITE(q, 1)
;     __syncthreads();
;     if (kt + 3 < nt) A_LOAD(q, (kt + 3) << 6)
;     A_TILE(1)
;     if (kt + 2 < nt) A_WRITE(p, 0)
;     __syncthreads();
;     if (kt + 4 < nt) A_LOAD(p, (kt + 4) << 6)
	s_waitcnt vmcnt(0)
	ds_write_b128 v241, v[176:179] offset:9216
	ds_write_b128 v242, v[180:183] offset:9216
	ds_write_b64 v244, v[212:213] offset:18432
	ds_write_b64 v244, v[214:215] offset:18440
	ds_write_b64 v245, v[216:217] offset:18432
	ds_write_b64 v245, v[218:219] offset:18440
	s_add_u32 s1, s68, 3
	s_add_u32 s10, s68, 2
	s_min_u32 s0, s1, 67
	s_mul_i32 s0, s0, 0x2000
	s_add_u32 s64, s60, s0
	s_addc_u32 s65, s61, 0
	s_min_u32 s0, s10, 67
	s_lshl_b32 s0, s0, 7
	s_add_u32 s66, s62, s0
	s_addc_u32 s67, s63, 0
	global_load_dwordx4 v[176:179], v246, s[64:65]
	global_load_dwordx4 v[180:183], v247, s[64:65]
	global_load_dwordx4 v[212:215], v249, s[66:67]
	global_load_dwordx4 v[216:219], v250, s[66:67]
	ds_read_b128 v[144:147], v238 offset:0
	ds_read_b128 v[148:151], v238 offset:4608
	ds_read_b128 v[152:155], v238 offset:32
	ds_read_b128 v[156:159], v238 offset:4640
	v_max3_f32 v223, v64, v65, v66
	v_max3_f32 v224, v72, v73, v74
	v_max3_f32 v225, v80, v81, v82
	v_max3_f32 v226, v88, v89, v90
	v_max3_f32 v223, v223, v67, v68
	v_max3_f32 v224, v224, v75, v76
	v_max3_f32 v225, v225, v83, v84
	v_max3_f32 v226, v226, v91, v92
	v_max3_f32 v223, v223, v69, v70
	s_waitcnt lgkmcnt(3)
	v_mfma_f32_32x32x16_bf16 v[32:47], v[144:147], v[112:115], 0
	ds_read_b128 v[144:147], v238 offset:64
	v_max3_f32 v224, v224, v77, v78
	v_max3_f32 v225, v225, v85, v86
	v_max3_f32 v226, v226, v93, v94
	v_max_f32_e32 v223, v223, v71
	v_max_f32_e32 v224, v224, v79
	v_max_f32_e32 v225, v225, v87
	v_max_f32_e32 v226, v226, v95
	v_max3_f32 v222, v223, v224, v225
	v_max_f32_e32 v222, v222, v226
	s_waitcnt lgkmcnt(3)
	v_mfma_f32_32x32x16_bf16 v[48:63], v[148:151], v[112:115], 0
	ds_read_b128 v[148:151], v238 offset:4672
	v_mov_b32_e32 v227, v222
	v_add_f32_e32 v228, 0x41000000, v220
	s_nop 0
	v_permlane32_swap_b32_e32 v222, v227
	v_max_f32_e32 v222, v222, v227
	v_cmp_gt_f32_e32 vcc, v222, v228
	s_cbranch_vccz .Lat_nors_5
	v_max_f32_e32 v229, v220, v222
	v_sub_f32_e32 v230, v220, v229
	v_exp_f32_e32 v230, v230
	v_mov_b32_e32 v220, v229
	s_nop 0
	v_mul_f32_e32 v221, v221, v230
	v_mul_f32_e32 v0, v0, v230
	v_mul_f32_e32 v1, v1, v230
	v_mul_f32_e32 v2, v2, v230
	v_mul_f32_e32 v3, v3, v230
	v_mul_f32_e32 v4, v4, v230
	v_mul_f32_e32 v5, v5, v230
	v_mul_f32_e32 v6, v6, v230
	v_mul_f32_e32 v7, v7, v230
	v_mul_f32_e32 v8, v8, v230
	v_mul_f32_e32 v9, v9, v230
	v_mul_f32_e32 v10, v10, v230
	v_mul_f32_e32 v11, v11, v230
	v_mul_f32_e32 v12, v12, v230
	v_mul_f32_e32 v13, v13, v230
	v_mul_f32_e32 v14, v14, v230
	v_mul_f32_e32 v15, v15, v230
	v_mul_f32_e32 v16, v16, v230
	v_mul_f32_e32 v17, v17, v230
	v_mul_f32_e32 v18, v18, v230
	v_mul_f32_e32 v19, v19, v230
	v_mul_f32_e32 v20, v20, v230
	v_mul_f32_e32 v21, v21, v230
	v_mul_f32_e32 v22, v22, v230
	v_mul_f32_e32 v23, v23, v230
	v_mul_f32_e32 v24, v24, v230
	v_mul_f32_e32 v25, v25, v230
	v_mul_f32_e32 v26, v26, v230
	v_mul_f32_e32 v27, v27, v230
	v_mul_f32_e32 v28, v28, v230
	v_mul_f32_e32 v29, v29, v230
	v_mul_f32_e32 v30, v30, v230
	v_mul_f32_e32 v31, v31, v230
.Lat_nors_5:
	v_sub_f32_e32 v64, v64, v220
	v_sub_f32_e32 v65, v65, v220
	v_sub_f32_e32 v66, v66, v220
	s_waitcnt lgkmcnt(3)
	v_mfma_f32_32x32x16_bf16 v[32:47], v[152:155], v[116:119], v[32:47]
	ds_read_b128 v[152:155], v238 offset:96
	v_sub_f32_e32 v67, v67, v220
	v_sub_f32_e32 v68, v68, v220
	v_sub_f32_e32 v69, v69, v220
	v_sub_f32_e32 v70, v70, v220
	v_sub_f32_e32 v71, v71, v220
	v_sub_f32_e32 v72, v72, v220
	v_sub_f32_e32 v73, v73, v220
	v_sub_f32_e32 v74, v74, v220
	v_sub_f32_e32 v75, v75, v220
	s_waitcnt lgkmcnt(3)
	v_mfma_f32_32x32x16_bf16 v[48:63], v[156:159], v[116:119], v[48:63]
	ds_read_b128 v[156:159], v238 offset:4704
	v_sub_f32_e32 v76, v76, v220
	v_sub_f32_e32 v77, v77, v220
	v_sub_f32_e32 v78, v78, v220
	v_sub_f32_e32 v79, v79, v220
	v_sub_f32_e32 v80, v80, v220
	v_sub_f32_e32 v81, v81, v220
	v_sub_f32_e32 v82, v82, v220
	v_sub_f32_e32 v83, v83, v220
	v_sub_f32_e32 v84, v84, v220
	s_waitcnt lgkmcnt(3)
	v_mfma_f32_32x32x16_bf16 v[32:47], v[144:147], v[120:123], v[32:47]
	v_sub_f32_e32 v85, v85, v220
	v_sub_f32_e32 v86, v86, v220
	v_sub_f32_e32 v87, v87, v220
	v_sub_f32_e32 v88, v88, v220
	v_sub_f32_e32 v89, v89, v220
	v_sub_f32_e32 v90, v90, v220
	v_sub_f32_e32 v91, v91, v220
	v_sub_f32_e32 v92, v92, v220
	v_sub_f32_e32 v93, v93, v220
	s_waitcnt lgkmcnt(2)
	v_mfma_f32_32x32x16_bf16 v[48:63], v[148:151], v[120:123], v[48:63]
	v_sub_f32_e32 v94, v94, v220
	v_sub_f32_e32 v95, v95, v220
	v_exp_f32_e32 v64, v64
	v_exp_f32_e32 v65, v65
	v_exp_f32_e32 v66, v66
	v_exp_f32_e32 v67, v67
	v_exp_f32_e32 v68, v68
	v_exp_f32_e32 v69, v69
	v_exp_f32_e32 v70, v70
	s_waitcnt lgkmcnt(1)
	v_mfma_f32_32x32x16_bf16 v[32:47], v[152:155], v[124:127], v[32:47]
	v_exp_f32_e32 v71, v71
	v_exp_f32_e32 v72, v72
	v_exp_f32_e32 v73, v73
	v_exp_f32_e32 v74, v74
	v_exp_f32_e32 v75, v75
	v_exp_f32_e32 v76, v76
	v_exp_f32_e32 v77, v77
	v_exp_f32_e32 v78, v78
	v_exp_f32_e32 v79, v79
	s_waitcnt lgkmcnt(0)
	v_mfma_f32_32x32x16_bf16 v[48:63], v[156:159], v[124:127], v[48:63]
	v_exp_f32_e32 v80, v80
	v_exp_f32_e32 v81, v81
	v_exp_f32_e32 v82, v82
	v_exp_f32_e32 v83, v83
	v_exp_f32_e32 v84, v84
	v_exp_f32_e32 v85, v85
	v_exp_f32_e32 v86, v86
	v_exp_f32_e32 v87, v87
	v_exp_f32_e32 v88, v88
	v_exp_f32_e32 v89, v89
	v_exp_f32_e32 v90, v90
	v_exp_f32_e32 v91, v91
	v_exp_f32_e32 v92, v92
	v_exp_f32_e32 v93, v93
	v_exp_f32_e32 v94, v94
	v_exp_f32_e32 v95, v95
	v_add_u32_e32 v223, 0x6a00, v239
	v_add_u32_e32 v224, 0x6a00, v240
	ds_read2_b64 v[160:163], v223 offset0:0 offset1:2
	ds_read2_b64 v[164:167], v224 offset0:0 offset1:2
	ds_read2_b64 v[168:171], v223 offset0:4 offset1:6
	ds_read2_b64 v[172:175], v224 offset0:4 offset1:6
	v_cvt_pk_bf16_f32 v96, v64, v65
	v_cvt_pk_bf16_f32 v97, v66, v67
	v_cvt_pk_bf16_f32 v98, v68, v69
	v_cvt_pk_bf16_f32 v99, v70, v71
	v_add_f32_e32 v231, v64, v68
	v_add_f32_e32 v232, v65, v69
	v_add_f32_e32 v233, v66, v70
	v_add_f32_e32 v237, v67, v71
	s_waitcnt lgkmcnt(3)
; DI unsigned pack2(float lo, float hi) { f32x2_t v = {lo, hi}; bf16x2_t r = __builtin_convertvector(v, bf16x2_t); return __builtin_bit_cast(unsigned, r); }
; DI float xhalf_sum(float x) { auto r = __builtin_amdgcn_permlane32_swap(__float_as_uint(x), __float_as_uint(x), false, false); return __uint_as_float(r[0]) + __uint_as_float(r[1]); }
; template <int DQK>
; DI void attn_item(const bf16_t* __restrict__ Q, const bf16_t* __restrict__ Kp, const bf16_t* __restrict__ Vt, int q0, int nkeys,
;                   bf16_t* __restrict__ mix, int colbase, int b, char* smem) {
;     ...
;   l = xhalf_sum(l);
;   const float inv = 1.0f / l;
;   const int kp = q0 + wave * 32 + r;
;   bf16_t* orow = mix + (size_t)row_of(b, kp) * D + colbase;
; #pragma unroll
;   for (int g = 0; g < 4; ++g) {
;     uint2 w0, w1;
;     w0.x = pack2(o0[4 * g] * inv, o0[4 * g + 1] * inv); w0.y = pack2(o0[4 * g + 2] * inv, o0[4 * g + 3] * inv);
;     w1.x = pack2(o1[4 * g] * inv, o1[4 * g + 1] * inv); w1.y = pack2(o1[4 * g + 2] * inv, o1[4 * g + 3] * inv);
;     *(uint2*)(orow + 8 * g + 4 * h) = w0;
;     *(uint2*)(orow + 32 + 8 * g + 4 * h) = w1;
;   }
	v_mfma_f32_32x32x16_bf16 v[0:15], v[160:163], v[96:99], v[0:15]
	ds_read2_b64 v[160:163], v223 offset0:8 offset1:10
	s_waitcnt lgkmcnt(3)
	v_mfma_f32_32x32x16_bf16 v[16:31], v[164:167], v[96:99], v[16:31]
	ds_read2_b64 v[164:167], v224 offset0:8 offset1:10
	v_cvt_pk_bf16_f32 v100, v72, v73
	v_cvt_pk_bf16_f32 v101, v74, v75
	v_cvt_pk_bf16_f32 v102, v76, v77
	v_cvt_pk_bf16_f32 v103, v78, v79
	v_add_f32_e32 v231, v231, v72
	v_add_f32_e32 v232, v232, v73
	v_add_f32_e32 v233, v233, v74
	v_add_f32_e32 v237, v237, v75
	v_add_f32_e32 v231, v231, v76
	v_add_f32_e32 v232, v232, v77
	v_add_f32_e32 v233, v233, v78
	v_add_f32_e32 v237, v237, v79
	s_waitcnt lgkmcnt(3)
	v_mfma_f32_32x32x16_bf16 v[0:15], v[168:171], v[100:103], v[0:15]
	ds_read2_b64 v[168:171], v223 offset0:12 offset1:14
	s_waitcnt lgkmcnt(3)
	v_mfma_f32_32x32x16_bf16 v[16:31], v[172:175], v[100:103], v[16:31]
	ds_read2_b64 v[172:175], v224 offset0:12 offset1:14
	v_cvt_pk_bf16_f32 v104, v80, v81
	v_cvt_pk_bf16_f32 v105, v82, v83
	v_cvt_pk_bf16_f32 v106, v84, v85
	v_cvt_pk_bf16_f32 v107, v86, v87
	v_add_f32_e32 v231, v231, v80
	v_add_f32_e32 v232, v232, v81
	v_add_f32_e32 v233, v233, v82
	v_add_f32_e32 v237, v237, v83
	v_add_f32_e32 v231, v231, v84
	v_add_f32_e32 v232, v232, v85
	v_add_f32_e32 v233, v233, v86
	v_add_f32_e32 v237, v237, v87
	s_waitcnt lgkmcnt(3)
	v_mfma_f32_32x32x16_bf16 v[0:15], v[160:163], v[104:107], v[0:15]
	s_waitcnt lgkmcnt(2)
	v_mfma_f32_32x32x16_bf16 v[16:31], v[164:167], v[104:107], v[16:31]
	v_cvt_pk_bf16_f32 v108, v88, v89
	v_cvt_pk_bf16_f32 v109, v90, v91
	v_cvt_pk_bf16_f32 v110, v92, v93
	v_cvt_pk_bf16_f32 v111, v94, v95
	v_add_f32_e32 v231, v231, v88
	v_add_f32_e32 v232, v232, v89
	v_add_f32_e32 v233, v233, v90
	v_add_f32_e32 v237, v237, v91
	v_add_f32_e32 v231, v231, v92
	v_add_f32_e32 v232, v232, v93
	v_add_f32_e32 v233, v233, v94
	v_add_f32_e32 v237, v237, v95
	s_waitcnt lgkmcnt(1)
	v_mfma_f32_32x32x16_bf16 v[0:15], v[168:171], v[108:111], v[0:15]
	s_waitcnt lgkmcnt(0)
	v_mfma_f32_32x32x16_bf16 v[16:31], v[172:175], v[108:111], v[16:31]
	v_add_f32_e32 v231, v231, v232
	v_add_f32_e32 v233, v233, v237
	v_add_f32_e32 v231, v231, v233
	v_add_f32_e32 v221, v221, v231
	s_add_u32 s68, s68, 1
	s_waitcnt lgkmcnt(0)
	s_barrier
	s_cmp_lt_u32 s68, 68
	s_cbranch_scc1 .Lat_loop_g
	s_nop 7
	v_mov_b32_e32 v223, v221
	s_nop 1
	v_permlane32_swap_b32_e32 v221, v223
	v_add_f32_e32 v221, v221, v223
	v_rcp_f32_e32 v224, v221
	s_nop 0
	v_mul_f32_e32 v160, v0, v224
	v_mul_f32_e32 v161, v1, v224
	v_mul_f32_e32 v162, v2, v224
	v_mul_f32_e32 v163, v3, v224
	v_cvt_pk_bf16_f32 v144, v160, v161
	v_cvt_pk_bf16_f32 v145, v162, v163
	global_store_dwordx2 v252, v[144:145], s[72:73] offset:0
	v_mul_f32_e32 v160, v16, v224
	v_mul_f32_e32 v161, v17, v224
	v_mul_f32_e32 v162, v18, v224
	v_mul_f32_e32 v163, v19, v224
	v_cvt_pk_bf16_f32 v146, v160, v161
	v_cvt_pk_bf16_f32 v147, v162, v163
	global_store_dwordx2 v252, v[146:147], s[72:73] offset:64
	v_mul_f32_e32 v160, v4, v224
	v_mul_f32_e32 v161, v5, v224
	v_mul_f32_e32 v162, v6, v224
	v_mul_f32_e32 v163, v7, v224
	v_cvt_pk_bf16_f32 v148, v160, v161
	v_cvt_pk_bf16_f32 v149, v162, v163
	global_store_dwordx2 v252, v[148:149], s[72:73] offset:16
	v_mul_f32_e32 v160, v20, v224
	v_mul_f32_e32 v161, v21, v224
	v_mul_f32_e32 v162, v22, v224
	v_mul_f32_e32 v163, v23, v224
	v_cvt_pk_bf16_f32 v150, v160, v161
	v_cvt_pk_bf16_f32 v151, v162, v163
	global_store_dwordx2 v252, v[150:151], s[72:73] offset:80
	v_mul_f32_e32 v160, v8, v224
	v_mul_f32_e32 v161, v9, v224
	v_mul_f32_e32 v162, v10, v224
	v_mul_f32_e32 v163, v11, v224
	v_cvt_pk_bf16_f32 v152, v160, v161
	v_cvt_pk_bf16_f32 v153, v162, v163
	global_store_dwordx2 v252, v[152:153], s[72:73] offset:32
	v_mul_f32_e32 v160, v24, v224
	v_mul_f32_e32 v161, v25, v224
	v_mul_f32_e32 v162, v26, v224
	v_mul_f32_e32 v163, v27, v224
	v_cvt_pk_bf16_f32 v154, v160, v161
	v_cvt_pk_bf16_f32 v155, v162, v163
	global_store_dwordx2 v252, v[154:155], s[72:73] offset:96
	v_mul_f32_e32 v160, v12, v224
	v_mul_f32_e32 v161, v13, v224
	v_mul_f32_e32 v162, v14, v224
	v_mul_f32_e32 v163, v15, v224
	v_cvt_pk_bf16_f32 v156, v160, v161
	v_cvt_pk_bf16_f32 v157, v162, v163
	global_store_dwordx2 v252, v[156:157], s[72:73] offset:48
	v_mul_f32_e32 v160, v28, v224
	v_mul_f32_e32 v161, v29, v224
	v_mul_f32_e32 v162, v30, v224
	v_mul_f32_e32 v163, v31, v224
	v_cvt_pk_bf16_f32 v158, v160, v161
	v_cvt_pk_bf16_f32 v159, v162, v163
	global_store_dwordx2 v252, v[158:159], s[72:73] offset:112
	s_branch .Lat_tyj_3
; template <int DQK>
; DI void attn_item(const bf16_t* __restrict__ Q, const bf16_t* __restrict__ Kp, const bf16_t* __restrict__ Vt, int q0, int nkeys,
;                   bf16_t* __restrict__ mix, int colbase, int b, char* smem) {
;     ...
;   bf16x8 qf[NSTEP];
;   {
;     const bf16_t* qr = Q + (size_t)(q0 + wave * 32 + r) * DQK + 8 * h;
; #pragma unroll
;     for (int s = 0; s < NSTEP; ++s) qf[s] = *(const bf16x8*)(qr + 16 * s);
;   }
;   const int kid0 = tid, kid1 = tid + 256, kid2 = tid + 512;
;   const int kgo0 = (kid0 / KCH) * DQK + (kid0 % KCH) * 8, kgo1 = (kid1 / KCH) * DQK + (kid1 % KCH) * 8, kgo2 = (kid2 / KCH) * DQK + (kid2 % KCH) * 8;
;   const int kso0 = (kid0 / KCH) * KROW + (kid0 % KCH) * 8, kso1 = (kid1 / KCH) * KROW + (kid1 % KCH) * 8, kso2 = (kid2 / KCH) * KROW + (kid2 % KCH) * 8;
;   const int vrow0 = tid >> 3, vcc = (tid & 7) * 8;
;   const bf16_t* Vg0 = Vt + (size_t)vrow0 * NKEY + vcc;
;   const bf16_t* Vg1 = Vt + (size_t)(vrow0 + 32) * NKEY + vcc;
;   const int vso0 = vrow0 * VROW + vcc, vso1 = (vrow0 + 32) * VROW + vcc;
; DI void attn_dispatch(const Params& p, int type, int b, int hd, int qb, char* smem) {
;     ...
;   } else {
;     const bf16_t* Q = (const bf16_t*)(p.ws + OFF_QM) + (size_t)(b * 6 + hd) * NKEY * 96;
;     const bf16_t* K = (const bf16_t*)(p.ws + OFF_KM) + (size_t)(b * 6 + hd) * NKEY * 96;
;     const bf16_t* V = (const bf16_t*)(p.ws + OFF_VMT) + (size_t)(b * 6 + hd) * 64 * NKEY;
;     attn_item<96>(Q, K, V, qb * 128, nkeys, MIX, 640 + hd * 64, b, smem);
.Lat_mla_2:
	s_mul_i32 s11, s54, 6
	s_add_u32 s11, s11, s55
	s_mul_i32 s28, s11, 0xcc000
	s_add_u32 s28, s28, 0xaa00000
	s_add_u32 s58, s24, s28
	s_addc_u32 s59, s25, 0
	s_mul_i32 s28, s11, 0xcc000
	s_add_u32 s28, s28, 0xd040000
	s_add_u32 s60, s24, s28
	s_addc_u32 s61, s25, 0
	s_mul_i32 s28, s11, 0x88000
	s_add_u32 s28, s28, 0xf680000
	s_add_u32 s62, s24, s28
	s_addc_u32 s63, s25, 0
	s_lshl_b32 s28, s55, 7
	s_add_u32 s28, s28, 0x500
	v_add_u32_e32 v252, s28, v252
	s_lshl_b32 s28, s57, 5
	s_add_u32 s28, s28, s56
	v_add_u32_e32 v251, s28, v253
	s_movk_i32 s29, 192
	v_mul_lo_u32 v251, v251, s29
	v_lshl_add_u32 v251, v140, 4, v251
	s_movk_i32 s29, 208
	v_mul_lo_u32 v238, v253, s29
	v_lshl_add_u32 v238, v140, 4, v238
	s_movk_i32 s29, 136
	v_mul_lo_u32 v239, v253, s29
	v_lshl_add_u32 v239, v140, 3, v239
	v_add_u32_e32 v240, 0x1100, v239
	v_mov_b32_e32 v225, v143
	s_mov_b32 s29, 0xaaab
	v_mul_u32_u24_e32 v226, 0xaaab, v225
	v_lshrrev_b32_e32 v226, 19, v226
	v_mul_u32_u24_e32 v227, 12, v226
	v_sub_u32_e32 v227, v225, v227
	s_movk_i32 s29, 192
	v_mul_lo_u32 v246, v226, s29
	v_lshl_add_u32 v246, v227, 4, v246
	s_movk_i32 s29, 208
	v_mul_lo_u32 v241, v226, s29
	v_lshl_add_u32 v241, v227, 4, v241
	v_add_u32_e32 v225, 256, v143
	s_mov_b32 s29, 0xaaab
	v_mul_u32_u24_e32 v226, 0xaaab, v225
	v_lshrrev_b32_e32 v226, 19, v226
	v_mul_u32_u24_e32 v227, 12, v226
	v_sub_u32_e32 v227, v225, v227
	s_movk_i32 s29, 192
	v_mul_lo_u32 v247, v226, s29
	v_lshl_add_u32 v247, v227, 4, v247
	s_movk_i32 s29, 208
	v_mul_lo_u32 v242, v226, s29
	v_lshl_add_u32 v242, v227, 4, v242
	v_add_u32_e32 v225, 512, v143
	s_mov_b32 s29, 0xaaab
	v_mul_u32_u24_e32 v226, 0xaaab, v225
	v_lshrrev_b32_e32 v226, 19, v226
	v_mul_u32_u24_e32 v227, 12, v226
	v_sub_u32_e32 v227, v225, v227
	s_movk_i32 s29, 192
	v_mul_lo_u32 v248, v226, s29
	v_lshl_add_u32 v248, v227, 4, v248
	s_movk_i32 s29, 208
	v_mul_lo_u32 v243, v226, s29
	v_lshl_add_u32 v243, v227, 4, v243
	v_lshrrev_b32_e32 v226, 3, v143
	v_and_b32_e32 v227, 7, v143
	s_movk_i32 s29, 8704
	v_mul_lo_u32 v249, v226, s29
	v_lshl_add_u32 v249, v227, 4, v249
	v_add_u32_e32 v250, 0x44000, v249
	s_movk_i32 s29, 136
	v_mul_lo_u32 v244, v226, s29
	v_lshl_add_u32 v244, v227, 4, v244
	v_add_u32_e32 v245, 0x1100, v244
	s_barrier
	global_load_dwordx4 v[112:115], v251, s[58:59] offset:0
	global_load_dwordx4 v[116:119], v251, s[58:59] offset:32
	global_load_dwordx4 v[120:123], v251, s[58:59] offset:64
	global_load_dwordx4 v[124:127], v251, s[58:59] offset:96
	global_load_dwordx4 v[128:131], v251, s[58:59] offset:128
	global_load_dwordx4 v[132:135], v251, s[58:59] offset:160
	s_mov_b32 s1, 0
	s_min_u32 s0, s1, 67
	s_mul_i32 s0, s0, 0x3000
	s_add_u32 s64, s60, s0
	s_addc_u32 s65, s61, 0
	s_min_u32 s0, s1, 67
	s_lshl_b32 s0, s0, 7
	s_add_u32 s66, s62, s0
	s_addc_u32 s67, s63, 0
	global_load_dwordx4 v[176:179], v246, s[64:65]
	global_load_dwordx4 v[180:183], v247, s[64:65]
	global_load_dwordx4 v[184:187], v248, s[64:65]
	global_load_dwordx4 v[212:215], v249, s[66:67]
	global_load_dwordx4 v[216:219], v250, s[66:67]
	s_waitcnt vmcnt(0)
	ds_write_b128 v241, v[176:179] offset:0
	ds_write_b128 v242, v[180:183] offset:0
	ds_write_b128 v243, v[184:187] offset:0
	ds_write_b64 v244, v[212:213] offset:26624
	ds_write_b64 v244, v[214:215] offset:26632
	ds_write_b64 v245, v[216:217] offset:26624
	ds_write_b64 v245, v[218:219] offset:26632
	s_mov_b32 s1, 1
	s_min_u32 s0, s1, 67
	s_mul_i32 s0, s0, 0x3000
	s_add_u32 s64, s60, s0
	s_addc_u32 s65, s61, 0
	s_min_u32 s0, s1, 67
	s_lshl_b32 s0, s0, 7
	s_add_u32 s66, s62, s0
	s_addc_u32 s67, s63, 0
	global_load_dwordx4 v[176:179], v246, s[64:65]
	global_load_dwordx4 v[180:183], v247, s[64:65]
	global_load_dwordx4 v[184:187], v248, s[64:65]
	s_waitcnt vmcnt(0)
	ds_write_b128 v241, v[176:179] offset:13312
	ds_write_b128 v242, v[180:183] offset:13312
	ds_write_b128 v243, v[184:187] offset:13312
	s_mov_b32 s1, 2
	s_mov_b32 s10, 1
	s_min_u32 s0, s1, 67
	s_mul_i32 s0, s0, 0x3000
	s_add_u32 s64, s60, s0
	s_addc_u32 s65, s61, 0
	s_min_u32 s0, s10, 67
	s_lshl_b32 s0, s0, 7
	s_add_u32 s66, s62, s0
	s_addc_u32 s67, s63, 0
	global_load_dwordx4 v[176:179], v246, s[64:65]
	global_load_dwordx4 v[180:183], v247, s[64:65]
	global_load_dwordx4 v[184:187], v248, s[64:65]
	global_load_dwordx4 v[212:215], v249, s[66:67]
	global_load_dwordx4 v[216:219], v250, s[66:67]
	v_mov_b32_e32 v0, 0
	v_mov_b32_e32 v1, 0
	v_mov_b32_e32 v2, 0
	v_mov_b32_e32 v3, 0
	v_mov_b32_e32 v4, 0
	v_mov_b32_e32 v5, 0
	v_mov_b32_e32 v6, 0
	v_mov_b32_e32 v7, 0
	v_mov_b32_e32 v8, 0
	v_mov_b32_e32 v9, 0
	v_mov_b32_e32 v10, 0
	v_mov_b32_e32 v11, 0
	v_mov_b32_e32 v12, 0
	v_mov_b32_e32 v13, 0
	v_mov_b32_e32 v14, 0
	v_mov_b32_e32 v15, 0
	v_mov_b32_e32 v16, 0
	v_mov_b32_e32 v17, 0
	v_mov_b32_e32 v18, 0
	v_mov_b32_e32 v19, 0
	v_mov_b32_e32 v20, 0
	v_mov_b32_e32 v21, 0
	v_mov_b32_e32 v22, 0
	v_mov_b32_e32 v23, 0
	v_mov_b32_e32 v24, 0
	v_mov_b32_e32 v25, 0
	v_mov_b32_e32 v26, 0
	v_mov_b32_e32 v27, 0
	v_mov_b32_e32 v28, 0
	v_mov_b32_e32 v29, 0
	v_mov_b32_e32 v30, 0
	v_mov_b32_e32 v31, 0
	v_mov_b32_e32 v220, 0xf149f2ca
	v_mov_b32_e32 v221, 0
	s_waitcnt lgkmcnt(0)
	s_barrier
	ds_read_b128 v[144:147], v238 offset:0
	ds_read_b128 v[148:151], v238 offset:6656
	ds_read_b128 v[152:155], v238 offset:32
	ds_read_b128 v[156:159], v238 offset:6688
	s_waitcnt lgkmcnt(3)
	v_mfma_f32_32x32x16_bf16 v[32:47], v[144:147], v[112:115], 0
	ds_read_b128 v[144:147], v238 offset:64
	s_waitcnt lgkmcnt(3)
	v_mfma_f32_32x32x16_bf16 v[48:63], v[148:151], v[112:115], 0
	ds_read_b128 v[148:151], v238 offset:6720
	s_waitcnt lgkmcnt(3)
	v_mfma_f32_32x32x16_bf16 v[32:47], v[152:155], v[116:119], v[32:47]
	ds_read_b128 v[152:155], v238 offset:96
	s_waitcnt lgkmcnt(3)
	v_mfma_f32_32x32x16_bf16 v[48:63], v[156:159], v[116:119], v[48:63]
	ds_read_b128 v[156:159], v238 offset:6752
	s_waitcnt lgkmcnt(3)
	v_mfma_f32_32x32x16_bf16 v[32:47], v[144:147], v[120:123], v[32:47]
	ds_read_b128 v[144:147], v238 offset:128
	s_waitcnt lgkmcnt(3)
	v_mfma_f32_32x32x16_bf16 v[48:63], v[148:151], v[120:123], v[48:63]
	ds_read_b128 v[148:151], v238 offset:6784
	s_waitcnt lgkmcnt(3)
	v_mfma_f32_32x32x16_bf16 v[32:47], v[152:155], v[124:127], v[32:47]
	ds_read_b128 v[152:155], v238 offset:160
	s_waitcnt lgkmcnt(3)
	v_mfma_f32_32x32x16_bf16 v[48:63], v[156:159], v[124:127], v[48:63]
	ds_read_b128 v[156:159], v238 offset:6816
	s_waitcnt lgkmcnt(3)
	v_mfma_f32_32x32x16_bf16 v[32:47], v[144:147], v[128:131], v[32:47]
	s_waitcnt lgkmcnt(2)
	v_mfma_f32_32x32x16_bf16 v[48:63], v[148:151], v[128:131], v[48:63]
	s_waitcnt lgkmcnt(1)
	v_mfma_f32_32x32x16_bf16 v[32:47], v[152:155], v[132:135], v[32:47]
	s_waitcnt lgkmcnt(0)
	v_mfma_f32_32x32x16_bf16 v[48:63], v[156:159], v[132:135], v[48:63]
	s_waitcnt lgkmcnt(0)
	s_barrier
	s_mov_b32 s68, 0
; template <int DQK>
; DI void attn_item(const bf16_t* __restrict__ Q, const bf16_t* __restrict__ Kp, const bf16_t* __restrict__ Vt, int q0, int nkeys,
;                   bf16_t* __restrict__ mix, int colbase, int b, char* smem) {
;     ...
;   for (int kt = 0; kt < nt; kt += 2) {
;     A_TILE(0)
;     A_WRITE(q, 1)
;     __syncthreads();
;     if (kt + 3 < nt) A_LOAD(q, (kt + 3) << 6)
.Lat_loop_m:
	s_waitcnt vmcnt(0)
	ds_write_b128 v241, v[176:179] offset:0
	ds_write_b128 v242, v[180:183] offset:0
	ds_write_b128 v243, v[184:187] offset:0
	ds_write_b64 v244, v[212:213] offset:35328
	ds_write_b64 v244, v[214:215] offset:35336
	ds_write_b64 v245, v[216:217] offset:35328
	ds_write_b64 v245, v[218:219] offset:35336
	s_add_u32 s1, s68, 3
	s_add_u32 s10, s68, 2
	s_min_u32 s0, s1, 67
	s_mul_i32 s0, s0, 0x3000
	s_add_u32 s64, s60, s0
	s_addc_u32 s65, s61, 0
	s_min_u32 s0, s10, 67
	s_lshl_b32 s0, s0, 7
	s_add_u32 s66, s62, s0
	s_addc_u32 s67, s63, 0
	global_load_dwordx4 v[176:179], v246, s[64:65]
	global_load_dwordx4 v[180:183], v247, s[64:65]
	global_load_dwordx4 v[184:187], v248, s[64:65]
	global_load_dwordx4 v[212:215], v249, s[66:67]
	global_load_dwordx4 v[216:219], v250, s[66:67]
	ds_read_b128 v[144:147], v238 offset:13312
	ds_read_b128 v[148:151], v238 offset:19968
	ds_read_b128 v[152:155], v238 offset:13344
	ds_read_b128 v[156:159], v238 offset:20000
	v_max3_f32 v223, v32, v33, v34
	v_max3_f32 v224, v40, v41, v42
	v_max3_f32 v225, v48, v49, v50
	v_max3_f32 v226, v56, v57, v58
	v_max3_f32 v223, v223, v35, v36
	v_max3_f32 v224, v224, v43, v44
	s_waitcnt lgkmcnt(3)
	v_mfma_f32_32x32x16_bf16 v[64:79], v[144:147], v[112:115], 0
	ds_read_b128 v[144:147], v238 offset:13376
	v_max3_f32 v225, v225, v51, v52
	v_max3_f32 v226, v226, v59, v60
	v_max3_f32 v223, v223, v37, v38
	v_max3_f32 v224, v224, v45, v46
	v_max3_f32 v225, v225, v53, v54
	v_max3_f32 v226, v226, v61, v62
	s_waitcnt lgkmcnt(3)
	v_mfma_f32_32x32x16_bf16 v[80:95], v[148:151], v[112:115], 0
	ds_read_b128 v[148:151], v238 offset:20032
	v_max_f32_e32 v223, v223, v39
	v_max_f32_e32 v224, v224, v47
	v_max_f32_e32 v225, v225, v55
	v_max_f32_e32 v226, v226, v63
	v_max3_f32 v222, v223, v224, v225
	v_max_f32_e32 v222, v222, v226
	s_waitcnt lgkmcnt(3)
	v_mfma_f32_32x32x16_bf16 v[64:79], v[152:155], v[116:119], v[64:79]
	ds_read_b128 v[152:155], v238 offset:13408
	v_mov_b32_e32 v227, v222
	v_add_f32_e32 v228, 0x41000000, v220
	s_nop 0
	v_permlane32_swap_b32_e32 v222, v227
	v_max_f32_e32 v222, v222, v227
	v_cmp_gt_f32_e32 vcc, v222, v228
	s_cbranch_vccz .Lat_nors_6
	v_max_f32_e32 v229, v220, v222
	v_sub_f32_e32 v230, v220, v229
	v_exp_f32_e32 v230, v230
	v_mov_b32_e32 v220, v229
	s_nop 0
	v_mul_f32_e32 v221, v221, v230
	v_mul_f32_e32 v0, v0, v230
	v_mul_f32_e32 v1, v1, v230
	v_mul_f32_e32 v2, v2, v230
	v_mul_f32_e32 v3, v3, v230
	v_mul_f32_e32 v4, v4, v230
	v_mul_f32_e32 v5, v5, v230
	v_mul_f32_e32 v6, v6, v230
	v_mul_f32_e32 v7, v7, v230
	v_mul_f32_e32 v8, v8, v230
	v_mul_f32_e32 v9, v9, v230
	v_mul_f32_e32 v10, v10, v230
	v_mul_f32_e32 v11, v11, v230
	v_mul_f32_e32 v12, v12, v230
	v_mul_f32_e32 v13, v13, v230
	v_mul_f32_e32 v14, v14, v230
	v_mul_f32_e32 v15, v15, v230
	v_mul_f32_e32 v16, v16, v230
	v_mul_f32_e32 v17, v17, v230
	v_mul_f32_e32 v18, v18, v230
	v_mul_f32_e32 v19, v19, v230
	v_mul_f32_e32 v20, v20, v230
	v_mul_f32_e32 v21, v21, v230
	v_mul_f32_e32 v22, v22, v230
	v_mul_f32_e32 v23, v23, v230
	v_mul_f32_e32 v24, v24, v230
	v_mul_f32_e32 v25, v25, v230
	v_mul_f32_e32 v26, v26, v230
	v_mul_f32_e32 v27, v27, v230
	v_mul_f32_e32 v28, v28, v230
	v_mul_f32_e32 v29, v29, v230
	v_mul_f32_e32 v30, v30, v230
	v_mul_f32_e32 v31, v31, v230
.Lat_nors_6:
	s_waitcnt lgkmcnt(3)
	v_mfma_f32_32x32x16_bf16 v[80:95], v[156:159], v[116:119], v[80:95]
	ds_read_b128 v[156:159], v238 offset:20064
	v_sub_f32_e32 v32, v32, v220
	v_sub_f32_e32 v33, v33, v220
	v_sub_f32_e32 v34, v34, v220
	v_sub_f32_e32 v35, v35, v220
	v_sub_f32_e32 v36, v36, v220
	v_sub_f32_e32 v37, v37, v220
	s_waitcnt lgkmcnt(3)
	v_mfma_f32_32x32x16_bf16 v[64:79], v[144:147], v[120:123], v[64:79]
	ds_read_b128 v[144:147], v238 offset:13440
	v_sub_f32_e32 v38, v38, v220
	v_sub_f32_e32 v39, v39, v220
	v_sub_f32_e32 v40, v40, v220
	v_sub_f32_e32 v41, v41, v220
	v_sub_f32_e32 v42, v42, v220
	v_sub_f32_e32 v43, v43, v220
	s_waitcnt lgkmcnt(3)
	v_mfma_f32_32x32x16_bf16 v[80:95], v[148:151], v[120:123], v[80:95]
	ds_read_b128 v[148:151], v238 offset:20096
	v_sub_f32_e32 v44, v44, v220
	v_sub_f32_e32 v45, v45, v220
	v_sub_f32_e32 v46, v46, v220
	v_sub_f32_e32 v47, v47, v220
	v_sub_f32_e32 v48, v48, v220
	v_sub_f32_e32 v49, v49, v220
	s_waitcnt lgkmcnt(3)
	v_mfma_f32_32x32x16_bf16 v[64:79], v[152:155], v[124:127], v[64:79]
	ds_read_b128 v[152:155], v238 offset:13472
	v_sub_f32_e32 v50, v50, v220
	v_sub_f32_e32 v51, v51, v220
	v_sub_f32_e32 v52, v52, v220
	v_sub_f32_e32 v53, v53, v220
	v_sub_f32_e32 v54, v54, v220
	v_sub_f32_e32 v55, v55, v220
	s_waitcnt lgkmcnt(3)
	v_mfma_f32_32x32x16_bf16 v[80:95], v[156:159], v[124:127], v[80:95]
	ds_read_b128 v[156:159], v238 offset:20128
	v_sub_f32_e32 v56, v56, v220
	v_sub_f32_e32 v57, v57, v220
	v_sub_f32_e32 v58, v58, v220
	v_sub_f32_e32 v59, v59, v220
	v_sub_f32_e32 v60, v60, v220
	v_sub_f32_e32 v61, v61, v220
	s_waitcnt lgkmcnt(3)
	v_mfma_f32_32x32x16_bf16 v[64:79], v[144:147], v[128:131], v[64:79]
	v_sub_f32_e32 v62, v62, v220
	v_sub_f32_e32 v63, v63, v220
	v_exp_f32_e32 v32, v32
	v_exp_f32_e32 v33, v33
	v_exp_f32_e32 v34, v34
	v_exp_f32_e32 v35, v35
	s_waitcnt lgkmcnt(2)
	v_mfma_f32_32x32x16_bf16 v[80:95], v[148:151], v[128:131], v[80:95]
	v_exp_f32_e32 v36, v36
	v_exp_f32_e32 v37, v37
	v_exp_f32_e32 v38, v38
	v_exp_f32_e32 v39, v39
	v_exp_f32_e32 v40, v40
	v_exp_f32_e32 v41, v41
	s_waitcnt lgkmcnt(1)
	v_mfma_f32_32x32x16_bf16 v[64:79], v[152:155], v[132:135], v[64:79]
	v_exp_f32_e32 v42, v42
	v_exp_f32_e32 v43, v43
	v_exp_f32_e32 v44, v44
	v_exp_f32_e32 v45, v45
	v_exp_f32_e32 v46, v46
	v_exp_f32_e32 v47, v47
	s_waitcnt lgkmcnt(0)
; template <int DQK>
; DI void attn_item(const bf16_t* __restrict__ Q, const bf16_t* __restrict__ Kp, const bf16_t* __restrict__ Vt, int q0, int nkeys,
;                   bf16_t* __restrict__ mix, int colbase, int b, char* smem) {
;     ...
;   const int nt = nkeys >> 6;
;   A_LOAD(p, 0)
;   A_LOAD(q, 64)
;   A_WRITE(p, 0)
;   __syncthreads();
;   if (nt > 2) A_LOAD(p, 128)
;   for (int kt = 0; kt < nt; kt += 2) {
;     A_TILE(0)
;     A_WRITE(q, 1)
;     __syncthreads();
;     if (kt + 3 < nt) A_LOAD(q, (kt + 3) << 6)
;     A_TILE(1)
;     if (kt + 2 < nt) A_WRITE(p, 0)
;     __syncthreads();
;     if (kt + 4 < nt) A_LOAD(p, (kt + 4) << 6)
	v_mfma_f32_32x32x16_bf16 v[80:95], v[156:159], v[132:135], v[80:95]
	v_exp_f32_e32 v48, v48
	v_exp_f32_e32 v49, v49
	v_exp_f32_e32 v50, v50
	v_exp_f32_e32 v51, v51
	v_exp_f32_e32 v52, v52
	v_exp_f32_e32 v53, v53
	v_exp_f32_e32 v54, v54
	v_exp_f32_e32 v55, v55
	v_exp_f32_e32 v56, v56
	v_exp_f32_e32 v57, v57
	v_exp_f32_e32 v58, v58
	v_exp_f32_e32 v59, v59
	v_exp_f32_e32 v60, v60
	v_exp_f32_e32 v61, v61
	v_exp_f32_e32 v62, v62
	v_exp_f32_e32 v63, v63
	v_add_u32_e32 v223, 0x6800, v239
	v_add_u32_e32 v224, 0x6800, v240
	ds_read2_b64 v[160:163], v223 offset0:0 offset1:2
	ds_read2_b64 v[164:167], v224 offset0:0 offset1:2
	ds_read2_b64 v[168:171], v223 offset0:4 offset1:6
	ds_read2_b64 v[172:175], v224 offset0:4 offset1:6
	v_cvt_pk_bf16_f32 v96, v32, v33
	v_cvt_pk_bf16_f32 v97, v34, v35
	v_cvt_pk_bf16_f32 v98, v36, v37
	v_cvt_pk_bf16_f32 v99, v38, v39
	v_add_f32_e32 v231, v32, v36
	v_add_f32_e32 v232, v33, v37
	v_add_f32_e32 v233, v34, v38
	v_add_f32_e32 v237, v35, v39
	s_waitcnt lgkmcnt(3)
	v_mfma_f32_32x32x16_bf16 v[0:15], v[160:163], v[96:99], v[0:15]
	ds_read2_b64 v[160:163], v223 offset0:8 offset1:10
	s_waitcnt lgkmcnt(3)
	v_mfma_f32_32x32x16_bf16 v[16:31], v[164:167], v[96:99], v[16:31]
	ds_read2_b64 v[164:167], v224 offset0:8 offset1:10
	v_cvt_pk_bf16_f32 v100, v40, v41
	v_cvt_pk_bf16_f32 v101, v42, v43
	v_cvt_pk_bf16_f32 v102, v44, v45
	v_cvt_pk_bf16_f32 v103, v46, v47
	v_add_f32_e32 v231, v231, v40
	v_add_f32_e32 v232, v232, v41
	v_add_f32_e32 v233, v233, v42
	v_add_f32_e32 v237, v237, v43
	v_add_f32_e32 v231, v231, v44
	v_add_f32_e32 v232, v232, v45
	v_add_f32_e32 v233, v233, v46
	v_add_f32_e32 v237, v237, v47
	s_waitcnt lgkmcnt(3)
	v_mfma_f32_32x32x16_bf16 v[0:15], v[168:171], v[100:103], v[0:15]
	ds_read2_b64 v[168:171], v223 offset0:12 offset1:14
	s_waitcnt lgkmcnt(3)
	v_mfma_f32_32x32x16_bf16 v[16:31], v[172:175], v[100:103], v[16:31]
	ds_read2_b64 v[172:175], v224 offset0:12 offset1:14
	v_cvt_pk_bf16_f32 v104, v48, v49
	v_cvt_pk_bf16_f32 v105, v50, v51
	v_cvt_pk_bf16_f32 v106, v52, v53
	v_cvt_pk_bf16_f32 v107, v54, v55
	v_add_f32_e32 v231, v231, v48
	v_add_f32_e32 v232, v232, v49
	v_add_f32_e32 v233, v233, v50
	v_add_f32_e32 v237, v237, v51
	v_add_f32_e32 v231, v231, v52
	v_add_f32_e32 v232, v232, v53
	v_add_f32_e32 v233, v233, v54
	v_add_f32_e32 v237, v237, v55
	s_waitcnt lgkmcnt(3)
	v_mfma_f32_32x32x16_bf16 v[0:15], v[160:163], v[104:107], v[0:15]
	s_waitcnt lgkmcnt(2)
	v_mfma_f32_32x32x16_bf16 v[16:31], v[164:167], v[104:107], v[16:31]
	v_cvt_pk_bf16_f32 v108, v56, v57
	v_cvt_pk_bf16_f32 v109, v58, v59
	v_cvt_pk_bf16_f32 v110, v60, v61
	v_cvt_pk_bf16_f32 v111, v62, v63
	v_add_f32_e32 v231, v231, v56
	v_add_f32_e32 v232, v232, v57
	v_add_f32_e32 v233, v233, v58
	v_add_f32_e32 v237, v237, v59
	v_add_f32_e32 v231, v231, v60
	v_add_f32_e32 v232, v232, v61
	v_add_f32_e32 v233, v233, v62
	v_add_f32_e32 v237, v237, v63
	s_waitcnt lgkmcnt(1)
	v_mfma_f32_32x32x16_bf16 v[0:15], v[168:171], v[108:111], v[0:15]
	s_waitcnt lgkmcnt(0)
	v_mfma_f32_32x32x16_bf16 v[16:31], v[172:175], v[108:111], v[16:31]
	v_add_f32_e32 v231, v231, v232
	v_add_f32_e32 v233, v233, v237
	v_add_f32_e32 v231, v231, v233
	v_add_f32_e32 v221, v221, v231
	s_add_u32 s68, s68, 1
	s_waitcnt lgkmcnt(0)
	s_barrier
	s_waitcnt vmcnt(0)
	ds_write_b128 v241, v[176:179] offset:13312
	ds_write_b128 v242, v[180:183] offset:13312
	ds_write_b128 v243, v[184:187] offset:13312
	ds_write_b64 v244, v[212:213] offset:26624
	ds_write_b64 v244, v[214:215] offset:26632
	ds_write_b64 v245, v[216:217] offset:26624
	ds_write_b64 v245, v[218:219] offset:26632
	s_add_u32 s1, s68, 3
	s_add_u32 s10, s68, 2
	s_min_u32 s0, s1, 67
	s_mul_i32 s0, s0, 0x3000
	s_add_u32 s64, s60, s0
	s_addc_u32 s65, s61, 0
	s_min_u32 s0, s10, 67
	s_lshl_b32 s0, s0, 7
	s_add_u32 s66, s62, s0
	s_addc_u32 s67, s63, 0
	global_load_dwordx4 v[176:179], v246, s[64:65]
	global_load_dwordx4 v[180:183], v247, s[64:65]
	global_load_dwordx4 v[184:187], v248, s[64:65]
	global_load_dwordx4 v[212:215], v249, s[66:67]
	global_load_dwordx4 v[216:219], v250, s[66:67]
	ds_read_b128 v[144:147], v238 offset:0
	ds_read_b128 v[148:151], v238 offset:6656
	ds_read_b128 v[152:155], v238 offset:32
	ds_read_b128 v[156:159], v238 offset:6688
	v_max3_f32 v223, v64, v65, v66
	v_max3_f32 v224, v72, v73, v74
	v_max3_f32 v225, v80, v81, v82
	v_max3_f32 v226, v88, v89, v90
	v_max3_f32 v223, v223, v67, v68
	v_max3_f32 v224, v224, v75, v76
	s_waitcnt lgkmcnt(3)
	v_mfma_f32_32x32x16_bf16 v[32:47], v[144:147], v[112:115], 0
	ds_read_b128 v[144:147], v238 offset:64
	v_max3_f32 v225, v225, v83, v84
	v_max3_f32 v226, v226, v91, v92
	v_max3_f32 v223, v223, v69, v70
	v_max3_f32 v224, v224, v77, v78
	v_max3_f32 v225, v225, v85, v86
	v_max3_f32 v226, v226, v93, v94
	s_waitcnt lgkmcnt(3)
	v_mfma_f32_32x32x16_bf16 v[48:63], v[148:151], v[112:115], 0
	ds_read_b128 v[148:151], v238 offset:6720
	v_max_f32_e32 v223, v223, v71
	v_max_f32_e32 v224, v224, v79
	v_max_f32_e32 v225, v225, v87
	v_max_f32_e32 v226, v226, v95
	v_max3_f32 v222, v223, v224, v225
	v_max_f32_e32 v222, v222, v226
	s_waitcnt lgkmcnt(3)
	v_mfma_f32_32x32x16_bf16 v[32:47], v[152:155], v[116:119], v[32:47]
	ds_read_b128 v[152:155], v238 offset:96
	v_mov_b32_e32 v227, v222
	v_add_f32_e32 v228, 0x41000000, v220
	s_nop 0
	v_permlane32_swap_b32_e32 v222, v227
	v_max_f32_e32 v222, v222, v227
	v_cmp_gt_f32_e32 vcc, v222, v228
	s_cbranch_vccz .Lat_nors_7
	v_max_f32_e32 v229, v220, v222
	v_sub_f32_e32 v230, v220, v229
	v_exp_f32_e32 v230, v230
	v_mov_b32_e32 v220, v229
	s_nop 0
	v_mul_f32_e32 v221, v221, v230
	v_mul_f32_e32 v0, v0, v230
	v_mul_f32_e32 v1, v1, v230
	v_mul_f32_e32 v2, v2, v230
	v_mul_f32_e32 v3, v3, v230
	v_mul_f32_e32 v4, v4, v230
	v_mul_f32_e32 v5, v5, v230
	v_mul_f32_e32 v6, v6, v230
	v_mul_f32_e32 v7, v7, v230
	v_mul_f32_e32 v8, v8, v230
	v_mul_f32_e32 v9, v9, v230
	v_mul_f32_e32 v10, v10, v230
	v_mul_f32_e32 v11, v11, v230
	v_mul_f32_e32 v12, v12, v230
	v_mul_f32_e32 v13, v13, v230
	v_mul_f32_e32 v14, v14, v230
	v_mul_f32_e32 v15, v15, v230
	v_mul_f32_e32 v16, v16, v230
	v_mul_f32_e32 v17, v17, v230
	v_mul_f32_e32 v18, v18, v230
	v_mul_f32_e32 v19, v19, v230
	v_mul_f32_e32 v20, v20, v230
	v_mul_f32_e32 v21, v21, v230
	v_mul_f32_e32 v22, v22, v230
	v_mul_f32_e32 v23, v23, v230
	v_mul_f32_e32 v24, v24, v230
	v_mul_f32_e32 v25, v25, v230
	v_mul_f32_e32 v26, v26, v230
	v_mul_f32_e32 v27, v27, v230
	v_mul_f32_e32 v28, v28, v230
	v_mul_f32_e32 v29, v29, v230
	v_mul_f32_e32 v30, v30, v230
	v_mul_f32_e32 v31, v31, v230
.Lat_nors_7:
	s_waitcnt lgkmcnt(3)
	v_mfma_f32_32x32x16_bf16 v[48:63], v[156:159], v[116:119], v[48:63]
	ds_read_b128 v[156:159], v238 offset:6752
	v_sub_f32_e32 v64, v64, v220
	v_sub_f32_e32 v65, v65, v220
	v_sub_f32_e32 v66, v66, v220
	v_sub_f32_e32 v67, v67, v220
	v_sub_f32_e32 v68, v68, v220
	v_sub_f32_e32 v69, v69, v220
	s_waitcnt lgkmcnt(3)
	v_mfma_f32_32x32x16_bf16 v[32:47], v[144:147], v[120:123], v[32:47]
	ds_read_b128 v[144:147], v238 offset:128
	v_sub_f32_e32 v70, v70, v220
	v_sub_f32_e32 v71, v71, v220
	v_sub_f32_e32 v72, v72, v220
	v_sub_f32_e32 v73, v73, v220
	v_sub_f32_e32 v74, v74, v220
	v_sub_f32_e32 v75, v75, v220
	s_waitcnt lgkmcnt(3)
	v_mfma_f32_32x32x16_bf16 v[48:63], v[148:151], v[120:123], v[48:63]
	ds_read_b128 v[148:151], v238 offset:6784
	v_sub_f32_e32 v76, v76, v220
	v_sub_f32_e32 v77, v77, v220
	v_sub_f32_e32 v78, v78, v220
	v_sub_f32_e32 v79, v79, v220
	v_sub_f32_e32 v80, v80, v220
	v_sub_f32_e32 v81, v81, v220
	s_waitcnt lgkmcnt(3)
	v_mfma_f32_32x32x16_bf16 v[32:47], v[152:155], v[124:127], v[32:47]
	ds_read_b128 v[152:155], v238 offset:160
	v_sub_f32_e32 v82, v82, v220
	v_sub_f32_e32 v83, v83, v220
	v_sub_f32_e32 v84, v84, v220
	v_sub_f32_e32 v85, v85, v220
	v_sub_f32_e32 v86, v86, v220
	v_sub_f32_e32 v87, v87, v220
	s_waitcnt lgkmcnt(3)
	v_mfma_f32_32x32x16_bf16 v[48:63], v[156:159], v[124:127], v[48:63]
	ds_read_b128 v[156:159], v238 offset:6816
	v_sub_f32_e32 v88, v88, v220
	v_sub_f32_e32 v89, v89, v220
	v_sub_f32_e32 v90, v90, v220
	v_sub_f32_e32 v91, v91, v220
	v_sub_f32_e32 v92, v92, v220
	v_sub_f32_e32 v93, v93, v220
	s_waitcnt lgkmcnt(3)
	v_mfma_f32_32x32x16_bf16 v[32:47], v[144:147], v[128:131], v[32:47]
	v_sub_f32_e32 v94, v94, v220
	v_sub_f32_e32 v95, v95, v220
	v_exp_f32_e32 v64, v64
	v_exp_f32_e32 v65, v65
	v_exp_f32_e32 v66, v66
	v_exp_f32_e32 v67, v67
	s_waitcnt lgkmcnt(2)
	v_mfma_f32_32x32x16_bf16 v[48:63], v[148:151], v[128:131], v[48:63]
	v_exp_f32_e32 v68, v68
	v_exp_f32_e32 v69, v69
	v_exp_f32_e32 v70, v70
	v_exp_f32_e32 v71, v71
	v_exp_f32_e32 v72, v72
	v_exp_f32_e32 v73, v73
	s_waitcnt lgkmcnt(1)
	v_mfma_f32_32x32x16_bf16 v[32:47], v[152:155], v[132:135], v[32:47]
	v_exp_f32_e32 v74, v74
	v_exp_f32_e32 v75, v75
	v_exp_f32_e32 v76, v76
	v_exp_f32_e32 v77, v77
	v_exp_f32_e32 v78, v78
	v_exp_f32_e32 v79, v79
	s_waitcnt lgkmcnt(0)
	v_mfma_f32_32x32x16_bf16 v[48:63], v[156:159], v[132:135], v[48:63]
	v_exp_f32_e32 v80, v80
	v_exp_f32_e32 v81, v81
	v_exp_f32_e32 v82, v82
	v_exp_f32_e32 v83, v83
	v_exp_f32_e32 v84, v84
	v_exp_f32_e32 v85, v85
	v_exp_f32_e32 v86, v86
	v_exp_f32_e32 v87, v87
	v_exp_f32_e32 v88, v88
	v_exp_f32_e32 v89, v89
	v_exp_f32_e32 v90, v90
	v_exp_f32_e32 v91, v91
	v_exp_f32_e32 v92, v92
	v_exp_f32_e32 v93, v93
	v_exp_f32_e32 v94, v94
	v_exp_f32_e32 v95, v95
	v_add_u32_e32 v223, 0x8a00, v239
	v_add_u32_e32 v224, 0x8a00, v240
	ds_read2_b64 v[160:163], v223 offset0:0 offset1:2
	ds_read2_b64 v[164:167], v224 offset0:0 offset1:2
	ds_read2_b64 v[168:171], v223 offset0:4 offset1:6
	ds_read2_b64 v[172:175], v224 offset0:4 offset1:6
	v_cvt_pk_bf16_f32 v96, v64, v65
	v_cvt_pk_bf16_f32 v97, v66, v67
	v_cvt_pk_bf16_f32 v98, v68, v69
	v_cvt_pk_bf16_f32 v99, v70, v71
	v_add_f32_e32 v231, v64, v68
	v_add_f32_e32 v232, v65, v69
	v_add_f32_e32 v233, v66, v70
	v_add_f32_e32 v237, v67, v71
	s_waitcnt lgkmcnt(3)
	v_mfma_f32_32x32x16_bf16 v[0:15], v[160:163], v[96:99], v[0:15]
	ds_read2_b64 v[160:163], v223 offset0:8 offset1:10
	s_waitcnt lgkmcnt(3)
	v_mfma_f32_32x32x16_bf16 v[16:31], v[164:167], v[96:99], v[16:31]
	ds_read2_b64 v[164:167], v224 offset0:8 offset1:10
	v_cvt_pk_bf16_f32 v100, v72, v73
	v_cvt_pk_bf16_f32 v101, v74, v75
	v_cvt_pk_bf16_f32 v102, v76, v77
	v_cvt_pk_bf16_f32 v103, v78, v79
	v_add_f32_e32 v231, v231, v72
	v_add_f32_e32 v232, v232, v73
	v_add_f32_e32 v233, v233, v74
	v_add_f32_e32 v237, v237, v75
	v_add_f32_e32 v231, v231, v76
	v_add_f32_e32 v232, v232, v77
	v_add_f32_e32 v233, v233, v78
	v_add_f32_e32 v237, v237, v79
	s_waitcnt lgkmcnt(3)
	v_mfma_f32_32x32x16_bf16 v[0:15], v[168:171], v[100:103], v[0:15]
	ds_read2_b64 v[168:171], v223 offset0:12 offset1:14
	s_waitcnt lgkmcnt(3)
	v_mfma_f32_32x32x16_bf16 v[16:31], v[172:175], v[100:103], v[16:31]
	ds_read2_b64 v[172:175], v224 offset0:12 offset1:14
	v_cvt_pk_bf16_f32 v104, v80, v81
	v_cvt_pk_bf16_f32 v105, v82, v83
	v_cvt_pk_bf16_f32 v106, v84, v85
	v_cvt_pk_bf16_f32 v107, v86, v87
	v_add_f32_e32 v231, v231, v80
	v_add_f32_e32 v232, v232, v81
	v_add_f32_e32 v233, v233, v82
	v_add_f32_e32 v237, v237, v83
	v_add_f32_e32 v231, v231, v84
	v_add_f32_e32 v232, v232, v85
	v_add_f32_e32 v233, v233, v86
	v_add_f32_e32 v237, v237, v87
	s_waitcnt lgkmcnt(3)
	v_mfma_f32_32x32x16_bf16 v[0:15], v[160:163], v[104:107], v[0:15]
	s_waitcnt lgkmcnt(2)
	v_mfma_f32_32x32x16_bf16 v[16:31], v[164:167], v[104:107], v[16:31]
	v_cvt_pk_bf16_f32 v108, v88, v89
	v_cvt_pk_bf16_f32 v109, v90, v91
	v_cvt_pk_bf16_f32 v110, v92, v93
	v_cvt_pk_bf16_f32 v111, v94, v95
	v_add_f32_e32 v231, v231, v88
	v_add_f32_e32 v232, v232, v89
	v_add_f32_e32 v233, v233, v90
	v_add_f32_e32 v237, v237, v91
	v_add_f32_e32 v231, v231, v92
	v_add_f32_e32 v232, v232, v93
	v_add_f32_e32 v233, v233, v94
	v_add_f32_e32 v237, v237, v95
	s_waitcnt lgkmcnt(1)
	v_mfma_f32_32x32x16_bf16 v[0:15], v[168:171], v[108:111], v[0:15]
	s_waitcnt lgkmcnt(0)
	v_mfma_f32_32x32x16_bf16 v[16:31], v[172:175], v[108:111], v[16:31]
	v_add_f32_e32 v231, v231, v232
	v_add_f32_e32 v233, v233, v237
	v_add_f32_e32 v231, v231, v233
	v_add_f32_e32 v221, v221, v231
	s_add_u32 s68, s68, 1
	s_waitcnt lgkmcnt(0)
	s_barrier
; DI unsigned pack2(float lo, float hi) { f32x2_t v = {lo, hi}; bf16x2_t r = __builtin_convertvector(v, bf16x2_t); return __builtin_bit_cast(unsigned, r); }
; DI float xhalf_sum(float x) { auto r = __builtin_amdgcn_permlane32_swap(__float_as_uint(x), __float_as_uint(x), false, false); return __uint_as_float(r[0]) + __uint_as_float(r[1]); }
; template <int DQK>
; DI void attn_item(const bf16_t* __restrict__ Q, const bf16_t* __restrict__ Kp, const bf16_t* __restrict__ Vt, int q0, int nkeys,
;                   bf16_t* __restrict__ mix, int colbase, int b, char* smem) {
;     ...
;   l = xhalf_sum(l);
;   const float inv = 1.0f / l;
;   const int kp = q0 + wave * 32 + r;
;   bf16_t* orow = mix + (size_t)row_of(b, kp) * D + colbase;
; #pragma unroll
;   for (int g = 0; g < 4; ++g) {
;     uint2 w0, w1;
;     w0.x = pack2(o0[4 * g] * inv, o0[4 * g + 1] * inv); w0.y = pack2(o0[4 * g + 2] * inv, o0[4 * g + 3] * inv);
;     w1.x = pack2(o1[4 * g] * inv, o1[4 * g + 1] * inv); w1.y = pack2(o1[4 * g + 2] * inv, o1[4 * g + 3] * inv);
;     *(uint2*)(orow + 8 * g + 4 * h) = w0;
;     *(uint2*)(orow + 32 + 8 * g + 4 * h) = w1;
;   }
; DI void phase_attn(const Params& p, int layer, char* smem) {
;     ...
;   for (int it = blockIdx.x; it < n_lat + n_ctx; it += gridDim.x) {
	s_cmp_lt_u32 s68, 68
	s_cbranch_scc1 .Lat_loop_m
	s_nop 7
	v_mov_b32_e32 v223, v221
	s_nop 1
	v_permlane32_swap_b32_e32 v221, v223
	v_add_f32_e32 v221, v221, v223
	v_rcp_f32_e32 v224, v221
	s_nop 0
	v_mul_f32_e32 v160, v0, v224
	v_mul_f32_e32 v161, v1, v224
	v_mul_f32_e32 v162, v2, v224
	v_mul_f32_e32 v163, v3, v224
	v_cvt_pk_bf16_f32 v144, v160, v161
	v_cvt_pk_bf16_f32 v145, v162, v163
	global_store_dwordx2 v252, v[144:145], s[72:73] offset:0
	v_mul_f32_e32 v160, v16, v224
	v_mul_f32_e32 v161, v17, v224
	v_mul_f32_e32 v162, v18, v224
	v_mul_f32_e32 v163, v19, v224
	v_cvt_pk_bf16_f32 v146, v160, v161
	v_cvt_pk_bf16_f32 v147, v162, v163
	global_store_dwordx2 v252, v[146:147], s[72:73] offset:64
	v_mul_f32_e32 v160, v4, v224
	v_mul_f32_e32 v161, v5, v224
	v_mul_f32_e32 v162, v6, v224
	v_mul_f32_e32 v163, v7, v224
	v_cvt_pk_bf16_f32 v148, v160, v161
	v_cvt_pk_bf16_f32 v149, v162, v163
	global_store_dwordx2 v252, v[148:149], s[72:73] offset:16
	v_mul_f32_e32 v160, v20, v224
	v_mul_f32_e32 v161, v21, v224
	v_mul_f32_e32 v162, v22, v224
	v_mul_f32_e32 v163, v23, v224
	v_cvt_pk_bf16_f32 v150, v160, v161
	v_cvt_pk_bf16_f32 v151, v162, v163
	global_store_dwordx2 v252, v[150:151], s[72:73] offset:80
	v_mul_f32_e32 v160, v8, v224
	v_mul_f32_e32 v161, v9, v224
	v_mul_f32_e32 v162, v10, v224
	v_mul_f32_e32 v163, v11, v224
	v_cvt_pk_bf16_f32 v152, v160, v161
	v_cvt_pk_bf16_f32 v153, v162, v163
	global_store_dwordx2 v252, v[152:153], s[72:73] offset:32
	v_mul_f32_e32 v160, v24, v224
	v_mul_f32_e32 v161, v25, v224
	v_mul_f32_e32 v162, v26, v224
	v_mul_f32_e32 v163, v27, v224
	v_cvt_pk_bf16_f32 v154, v160, v161
	v_cvt_pk_bf16_f32 v155, v162, v163
	global_store_dwordx2 v252, v[154:155], s[72:73] offset:96
	v_mul_f32_e32 v160, v12, v224
	v_mul_f32_e32 v161, v13, v224
	v_mul_f32_e32 v162, v14, v224
	v_mul_f32_e32 v163, v15, v224
	v_cvt_pk_bf16_f32 v156, v160, v161
	v_cvt_pk_bf16_f32 v157, v162, v163
	global_store_dwordx2 v252, v[156:157], s[72:73] offset:48
	v_mul_f32_e32 v160, v28, v224
	v_mul_f32_e32 v161, v29, v224
	v_mul_f32_e32 v162, v30, v224
	v_mul_f32_e32 v163, v31, v224
	v_cvt_pk_bf16_f32 v158, v160, v161
	v_cvt_pk_bf16_f32 v159, v162, v163
	global_store_dwordx2 v252, v[158:159], s[72:73] offset:112
.Lat_tyj_3:
	s_add_u32 s52, s52, s26
	s_branch .Lat_item
.Lat_done:
	s_mov_b32 s0, s52
	v_readlane_b32 s52, v254, 0
	v_readlane_b32 s53, v254, 1
	v_readlane_b32 s54, v254, 2
	v_readlane_b32 s55, v254, 3
	v_readlane_b32 s56, v254, 4
	v_readlane_b32 s57, v254, 5
	v_readlane_b32 s58, v254, 6
	v_readlane_b32 s59, v254, 7
	v_readlane_b32 s60, v254, 8
	v_readlane_b32 s61, v254, 9
	v_readlane_b32 s62, v254, 10
	v_readlane_b32 s63, v254, 11
	v_readlane_b32 s64, v254, 12
	v_readlane_b32 s65, v254, 13
	v_readlane_b32 s66, v254, 14
	v_readlane_b32 s67, v254, 15
	v_readlane_b32 s68, v254, 16
	v_readlane_b32 s69, v254, 17
	v_readlane_b32 s70, v254, 18
	v_readlane_b32 s71, v254, 19
	v_readlane_b32 s72, v254, 20
	v_readlane_b32 s73, v254, 21
	v_readlane_b32 s74, v254, 22
	v_readlane_b32 s75, v254, 23
	v_readlane_b32 s76, v254, 24
	v_readlane_b32 s77, v254, 25
	v_readlane_b32 s78, v254, 26
	v_readlane_b32 s79, v254, 27
	v_readlane_b32 s80, v254, 28
	v_readlane_b32 s81, v254, 29
	v_readlane_b32 s82, v254, 30
	v_readlane_b32 s83, v254, 31
	v_readlane_b32 s84, v254, 32
	v_readlane_b32 s85, v254, 33
	v_readlane_b32 s86, v254, 34
	v_readlane_b32 s87, v254, 35
	v_readlane_b32 s88, v254, 36
	v_readlane_b32 s89, v254, 37
	v_readlane_b32 s90, v254, 38
	v_readlane_b32 s91, v254, 39
	s_nop 3
	s_mov_b32 s13, s0
	s_cmp_ge_i32 s13, s12
	s_cbranch_scc0 .LBB0_1453
	s_branch .LBB0_1446
